# more latency de-serialisation: EpiRes/EpiIn row-stat loads batched, gate-weight loops unrolled, x->bf16 copy 8 loads in flight, final LayerNorm loop with hoisted gain/bias and batched loads
# speedup vs baseline: 1.1232x; 1.0301x over previous
; #define PG8_STAGE(bufoff, gbase, voff) do { _Pragma("unroll") for (int _i = 0; _i < 2; ++_i) \
;         __builtin_amdgcn_global_load_lds((const unsigned*)((const char*)(gbase) + (voff)[_i]), (LAS unsigned*)(lds + (bufoff) + ldsw + _i * 8192), 16, 0, 0); } while (0)
; #define PG8_LDA(dst, b, h) do { _Pragma("unroll") for (int m = 0; m < 4; ++m) _Pragma("unroll") for (int k = 0; k < 2; ++k) dst[m][k] = *(const LAS bf16x8*)(lds + PG8_SA(b, h) + aoff + m * 2048 + k * 1024); } while (0)
; #define PG8_WAIT_V(n) asm volatile("s_waitcnt vmcnt(" #n ")" ::: "memory")
; #define PG8_WAIT_L(n) asm volatile("s_waitcnt lgkmcnt(" #n ")" ::: "memory")
; template <class Epi>
; __device__ __forceinline__ void gemm_phase(const Tb tb, LAS unsigned char* lds, const Gemm g, const StaticOrder& S, const Epi& E) {
;     ...
;         for (int t = 0; t < nt; t += 2) {
;             const bool last = (t == nt - 2);
;             const char* a1 = cA + (size_t)(t + 1) * kstep;
;             const char* a2 = last ? nA : cA + (size_t)(t + 2) * kstep; const char* b2 = last ? nB : cB + (size_t)(t + 2) * kstep;
;             const char* a3 = a2 + kstep; const char* b3 = b2 + kstep;
;             PG8_LDB(B0, 0, 0); PG8_SCHED; PG8_LDA(At, 0, 0); PG8_STAGE(PG8_SA(1, 1), a1 + hstep, voffA);
;             PG8_WAIT_L(8); PG8_BAR; PG8_WAIT_L(0); PG8_MMA(0, 0, At, B0); PG8_BAR; PG8_SCHED;
;             PG8_LDB(B1, 0, 1); PG8_STAGE(PG8_SB(0, 0), b2, voffB);
;             PG8_BAR; PG8_WAIT_L(0); PG8_MMA(0, 1, At, B1); PG8_BAR;
;             PG8_LDA(At, 0, 1); PG8_STAGE(PG8_SA(0, 0), a2, voffA);
;             PG8_BAR; PG8_WAIT_L(0); PG8_MMA(1, 0, At, B0); PG8_BAR; PG8_SCHED;
;             PG8_STAGE(PG8_SB(0, 1), b2 + hstep, voffB);
;             PG8_WAIT_V(6); PG8_BAR; PG8_MMA(1, 1, At, B1); PG8_BAR;
;             PG8_LDB(B0, 1, 0); PG8_SCHED; PG8_LDA(At, 1, 0); PG8_STAGE(PG8_SA(0, 1), a2 + hstep, voffA);
;             PG8_WAIT_L(8); PG8_BAR; PG8_WAIT_L(0); PG8_MMA(0, 0, At, B0); PG8_BAR; PG8_SCHED;
;             PG8_LDB(B1, 1, 1); PG8_STAGE(PG8_SB(1, 0), b3, voffB);
;             PG8_BAR; PG8_WAIT_L(0); PG8_MMA(0, 1, At, B1); PG8_BAR;
;             PG8_LDA(At, 1, 1); PG8_STAGE(PG8_SA(1, 0), a3, voffA);
;             PG8_BAR; PG8_WAIT_L(0); PG8_MMA(1, 0, At, B0); PG8_BAR; PG8_SCHED;
;             PG8_STAGE(PG8_SB(1, 1), b3 + hstep, voffB);
;             PG8_WAIT_V(6); PG8_BAR; PG8_MMA(1, 1, At, B1); PG8_BAR;
.LBB0_65:
	s_add_u32 s6, s26, 0x100
	s_addc_u32 s7, s27, 0
	s_add_i32 s58, 0, 0x10000
	v_add_u32_e32 v146, s58, v153
	ds_read_b128 v[134:137], v146
	ds_read_b128 v[138:141], v146 offset:1024
	ds_read_b128 v[142:145], v146 offset:2048
	ds_read_b128 v[146:149], v146 offset:3072
	s_cmp_eq_u32 s57, 40
	s_cselect_b32 s31, s25, s7
	s_cselect_b32 s30, s24, s6
	s_cselect_b32 s29, s9, s56
	s_cselect_b32 s28, s8, s55
	v_lshl_add_u64 v[150:151], s[26:27], 0, v[132:133]
	s_add_i32 m0, s42, 0xc000
	ds_read_b128 v[156:159], v155
	ds_read_b128 v[160:163], v155 offset:1024
	ds_read_b128 v[164:167], v155 offset:2048
	ds_read_b128 v[168:171], v155 offset:3072
	ds_read_b128 v[172:175], v155 offset:4096
	ds_read_b128 v[176:179], v155 offset:5120
	ds_read_b128 v[204:207], v155 offset:6144
	ds_read_b128 v[208:211], v155 offset:7168
	global_load_lds_dwordx4 v[150:151], off
	v_lshl_add_u64 v[150:151], s[26:27], 0, v[130:131]
	s_add_i32 m0, s42, 0xe000
	s_nop 0
	global_load_lds_dwordx4 v[150:151], off
	s_waitcnt lgkmcnt(8)
	s_barrier
	s_waitcnt lgkmcnt(0)
	s_setprio 1
	s_waitcnt lgkmcnt(0)
	v_mfma_f32_16x16x32_bf16 v[124:127], v[134:137], v[156:159], v[124:127]
	v_mfma_f32_16x16x32_bf16 v[120:123], v[142:145], v[156:159], v[120:123]
	v_mfma_f32_16x16x32_bf16 v[108:111], v[134:137], v[164:167], v[108:111]
	v_mfma_f32_16x16x32_bf16 v[104:107], v[142:145], v[164:167], v[104:107]
	v_mfma_f32_16x16x32_bf16 v[92:95], v[134:137], v[172:175], v[92:95]
	v_mfma_f32_16x16x32_bf16 v[88:91], v[142:145], v[172:175], v[88:91]
	v_mfma_f32_16x16x32_bf16 v[76:79], v[134:137], v[204:207], v[76:79]
	v_mfma_f32_16x16x32_bf16 v[72:75], v[142:145], v[204:207], v[72:75]
	v_mfma_f32_16x16x32_bf16 v[124:127], v[138:141], v[160:163], v[124:127]
	v_mfma_f32_16x16x32_bf16 v[120:123], v[146:149], v[160:163], v[120:123]
	v_mfma_f32_16x16x32_bf16 v[108:111], v[138:141], v[168:171], v[108:111]
	v_mfma_f32_16x16x32_bf16 v[104:107], v[146:149], v[168:171], v[104:107]
	v_mfma_f32_16x16x32_bf16 v[92:95], v[138:141], v[176:179], v[92:95]
	v_mfma_f32_16x16x32_bf16 v[88:91], v[146:149], v[176:179], v[88:91]
	v_mfma_f32_16x16x32_bf16 v[76:79], v[138:141], v[208:211], v[76:79]
	v_mfma_f32_16x16x32_bf16 v[72:75], v[146:149], v[208:211], v[72:75]
	s_setprio 0
	s_barrier
	s_add_i32 s59, 0, 0x14000
	v_add_u32_e32 v150, s59, v153
	s_add_i32 s26, s58, s41
	ds_read_b128 v[212:215], v150
	ds_read_b128 v[216:219], v150 offset:1024
	ds_read_b128 v[220:223], v150 offset:2048
	ds_read_b128 v[224:227], v150 offset:3072
	v_lshl_add_u64 v[150:151], s[28:29], 0, v[180:181]
	s_mov_b32 m0, s26
	v_lshl_add_u64 v[198:199], s[28:29], 0, v[128:129]
	global_load_lds_dwordx4 v[150:151], off
	s_add_i32 m0, s26, 0x2000
	s_nop 0
	global_load_lds_dwordx4 v[198:199], off
	s_barrier
	s_waitcnt lgkmcnt(0)
	s_setprio 1
	s_waitcnt lgkmcnt(0)
	v_mfma_f32_16x16x32_bf16 v[116:119], v[212:215], v[156:159], v[116:119]
	v_mfma_f32_16x16x32_bf16 v[112:115], v[220:223], v[156:159], v[112:115]
	v_mfma_f32_16x16x32_bf16 v[100:103], v[212:215], v[164:167], v[100:103]
	v_mfma_f32_16x16x32_bf16 v[96:99], v[220:223], v[164:167], v[96:99]
	v_mfma_f32_16x16x32_bf16 v[84:87], v[212:215], v[172:175], v[84:87]
	v_mfma_f32_16x16x32_bf16 v[80:83], v[220:223], v[172:175], v[80:83]
	v_mfma_f32_16x16x32_bf16 v[68:71], v[212:215], v[204:207], v[68:71]
	v_mfma_f32_16x16x32_bf16 v[64:67], v[220:223], v[204:207], v[64:67]
	v_mfma_f32_16x16x32_bf16 v[116:119], v[216:219], v[160:163], v[116:119]
	v_mfma_f32_16x16x32_bf16 v[112:115], v[224:227], v[160:163], v[112:115]
	v_mfma_f32_16x16x32_bf16 v[100:103], v[216:219], v[168:171], v[100:103]
	v_mfma_f32_16x16x32_bf16 v[96:99], v[224:227], v[168:171], v[96:99]
	v_mfma_f32_16x16x32_bf16 v[84:87], v[216:219], v[176:179], v[84:87]
	v_mfma_f32_16x16x32_bf16 v[80:83], v[224:227], v[176:179], v[80:83]
	v_mfma_f32_16x16x32_bf16 v[68:71], v[216:219], v[208:211], v[68:71]
	v_mfma_f32_16x16x32_bf16 v[64:67], v[224:227], v[208:211], v[64:67]
	s_setprio 0
	s_mov_b32 m0, s42
	v_lshl_add_u64 v[228:229], s[30:31], 0, v[180:181]
	s_barrier
	ds_read_b128 v[156:159], v155 offset:16384
	ds_read_b128 v[160:163], v155 offset:17408
	ds_read_b128 v[164:167], v155 offset:18432
	ds_read_b128 v[168:171], v155 offset:19456
	ds_read_b128 v[172:175], v155 offset:20480
	ds_read_b128 v[176:179], v155 offset:21504
	ds_read_b128 v[204:207], v155 offset:22528
	ds_read_b128 v[208:211], v155 offset:23552
	global_load_lds_dwordx4 v[228:229], off
	v_lshl_add_u64 v[230:231], s[30:31], 0, v[128:129]
	s_mov_b32 m0, s43
	s_nop 0
	global_load_lds_dwordx4 v[230:231], off
	s_barrier
	s_waitcnt lgkmcnt(0)
	s_setprio 1
	s_waitcnt lgkmcnt(0)
	v_mfma_f32_16x16x32_bf16 v[60:63], v[134:137], v[156:159], v[60:63]
	v_mfma_f32_16x16x32_bf16 v[56:59], v[142:145], v[156:159], v[56:59]
	v_mfma_f32_16x16x32_bf16 v[44:47], v[134:137], v[164:167], v[44:47]
	v_mfma_f32_16x16x32_bf16 v[40:43], v[142:145], v[164:167], v[40:43]
	v_mfma_f32_16x16x32_bf16 v[28:31], v[134:137], v[172:175], v[28:31]
	v_mfma_f32_16x16x32_bf16 v[24:27], v[142:145], v[172:175], v[24:27]
	v_mfma_f32_16x16x32_bf16 v[12:15], v[134:137], v[204:207], v[12:15]
	v_mfma_f32_16x16x32_bf16 v[8:11], v[142:145], v[204:207], v[8:11]
	v_mfma_f32_16x16x32_bf16 v[60:63], v[138:141], v[160:163], v[60:63]
	v_mfma_f32_16x16x32_bf16 v[56:59], v[146:149], v[160:163], v[56:59]
	v_mfma_f32_16x16x32_bf16 v[44:47], v[138:141], v[168:171], v[44:47]
	v_mfma_f32_16x16x32_bf16 v[40:43], v[146:149], v[168:171], v[40:43]
	v_mfma_f32_16x16x32_bf16 v[28:31], v[138:141], v[176:179], v[28:31]
	v_mfma_f32_16x16x32_bf16 v[24:27], v[146:149], v[176:179], v[24:27]
	v_mfma_f32_16x16x32_bf16 v[12:15], v[138:141], v[208:211], v[12:15]
	v_mfma_f32_16x16x32_bf16 v[8:11], v[146:149], v[208:211], v[8:11]
	s_setprio 0
	s_barrier
; #define PG8_STAGE(bufoff, gbase, voff) do { _Pragma("unroll") for (int _i = 0; _i < 2; ++_i) \
;         __builtin_amdgcn_global_load_lds((const unsigned*)((const char*)(gbase) + (voff)[_i]), (LAS unsigned*)(lds + (bufoff) + ldsw + _i * 8192), 16, 0, 0); } while (0)
; #define PG8_LDA(dst, b, h) do { _Pragma("unroll") for (int m = 0; m < 4; ++m) _Pragma("unroll") for (int k = 0; k < 2; ++k) dst[m][k] = *(const LAS bf16x8*)(lds + PG8_SA(b, h) + aoff + m * 2048 + k * 1024); } while (0)
; #define PG8_LDB(dst, b, h) do { _Pragma("unroll") for (int n = 0; n < 2; ++n) _Pragma("unroll") for (int k = 0; k < 2; ++k) dst[n][k] = *(const LAS bf16x8*)(lds + PG8_SB(b, h) + boff + n * 2048 + k * 1024); } while (0)
; #define PG8_WAIT_V(n) asm volatile("s_waitcnt vmcnt(" #n ")" ::: "memory")
; #define PG8_WAIT_L(n) asm volatile("s_waitcnt lgkmcnt(" #n ")" ::: "memory")
; #define PG8_BAR __builtin_amdgcn_s_barrier()
; #define PG8_SCHED __builtin_amdgcn_sched_barrier(0)
; template <class Epi>
; __device__ __forceinline__ void gemm_phase(const Tb tb, LAS unsigned char* lds, const Gemm g, const StaticOrder& S, const Epi& E) {
;     ...
;             PG8_LDB(B0, 0, 0); PG8_SCHED; PG8_LDA(At, 0, 0); PG8_STAGE(PG8_SA(1, 1), a1 + hstep, voffA);
;             PG8_WAIT_L(8); PG8_BAR; PG8_WAIT_L(0); PG8_MMA(0, 0, At, B0); PG8_BAR; PG8_SCHED;
;             PG8_LDB(B1, 0, 1); PG8_STAGE(PG8_SB(0, 0), b2, voffB);
;             PG8_BAR; PG8_WAIT_L(0); PG8_MMA(0, 1, At, B1); PG8_BAR;
;             PG8_LDA(At, 0, 1); PG8_STAGE(PG8_SA(0, 0), a2, voffA);
;             PG8_BAR; PG8_WAIT_L(0); PG8_MMA(1, 0, At, B0); PG8_BAR; PG8_SCHED;
;             PG8_STAGE(PG8_SB(0, 1), b2 + hstep, voffB);
;             PG8_WAIT_V(6); PG8_BAR; PG8_MMA(1, 1, At, B1); PG8_BAR;
;             PG8_LDB(B0, 1, 0); PG8_SCHED; PG8_LDA(At, 1, 0); PG8_STAGE(PG8_SA(0, 1), a2 + hstep, voffA);
;             PG8_WAIT_L(8); PG8_BAR; PG8_WAIT_L(0); PG8_MMA(0, 0, At, B0); PG8_BAR; PG8_SCHED;
;             PG8_LDB(B1, 1, 1); PG8_STAGE(PG8_SB(1, 0), b3, voffB);
;             PG8_BAR; PG8_WAIT_L(0); PG8_MMA(0, 1, At, B1); PG8_BAR;
;             PG8_LDA(At, 1, 1); PG8_STAGE(PG8_SA(1, 0), a3, voffA);
;             PG8_BAR; PG8_WAIT_L(0); PG8_MMA(1, 0, At, B0); PG8_BAR; PG8_SCHED;
;             PG8_STAGE(PG8_SB(1, 1), b3 + hstep, voffB);
;             PG8_WAIT_V(6); PG8_BAR; PG8_MMA(1, 1, At, B1); PG8_BAR;
	s_add_u32 s26, s28, 0xb0000
	s_addc_u32 s27, s29, 0
	s_add_i32 s58, s59, s41
	v_lshl_add_u64 v[134:135], s[26:27], 0, v[180:181]
	s_mov_b32 m0, s58
	s_nop 0
	global_load_lds_dwordx4 v[134:135], off
	v_lshl_add_u64 v[134:135], s[26:27], 0, v[128:129]
	s_add_i32 m0, s58, 0x2000
	s_nop 0
	global_load_lds_dwordx4 v[134:135], off
	s_waitcnt vmcnt(6)
	s_barrier
	s_setprio 1
	v_mfma_f32_16x16x32_bf16 v[52:55], v[212:215], v[156:159], v[52:55]
	v_mfma_f32_16x16x32_bf16 v[48:51], v[220:223], v[156:159], v[48:51]
	v_mfma_f32_16x16x32_bf16 v[36:39], v[212:215], v[164:167], v[36:39]
	v_mfma_f32_16x16x32_bf16 v[32:35], v[220:223], v[164:167], v[32:35]
	v_mfma_f32_16x16x32_bf16 v[20:23], v[212:215], v[172:175], v[20:23]
	v_mfma_f32_16x16x32_bf16 v[16:19], v[220:223], v[172:175], v[16:19]
	v_mfma_f32_16x16x32_bf16 v[4:7], v[212:215], v[204:207], v[4:7]
	v_mfma_f32_16x16x32_bf16 v[0:3], v[220:223], v[204:207], v[0:3]
	v_mfma_f32_16x16x32_bf16 v[52:55], v[216:219], v[160:163], v[52:55]
	v_mfma_f32_16x16x32_bf16 v[48:51], v[224:227], v[160:163], v[48:51]
	v_mfma_f32_16x16x32_bf16 v[36:39], v[216:219], v[168:171], v[36:39]
	v_mfma_f32_16x16x32_bf16 v[32:35], v[224:227], v[168:171], v[32:35]
	v_mfma_f32_16x16x32_bf16 v[20:23], v[216:219], v[176:179], v[20:23]
	v_mfma_f32_16x16x32_bf16 v[16:19], v[224:227], v[176:179], v[16:19]
	v_mfma_f32_16x16x32_bf16 v[4:7], v[216:219], v[208:211], v[4:7]
	v_mfma_f32_16x16x32_bf16 v[0:3], v[224:227], v[208:211], v[0:3]
	s_setprio 0
	s_add_i32 s58, 0, 0x18000
	v_add_u32_e32 v146, s58, v153
	s_barrier
	ds_read_b128 v[134:137], v146
	ds_read_b128 v[138:141], v146 offset:1024
	ds_read_b128 v[142:145], v146 offset:2048
	ds_read_b128 v[146:149], v146 offset:3072
	s_add_u32 s26, s30, 0xb0000
	s_addc_u32 s27, s31, 0
	s_mov_b32 m0, s44
	v_lshl_add_u64 v[212:213], s[26:27], 0, v[180:181]
	ds_read_b128 v[156:159], v155 offset:32768
	ds_read_b128 v[160:163], v155 offset:33792
	ds_read_b128 v[164:167], v155 offset:34816
	ds_read_b128 v[168:171], v155 offset:35840
	ds_read_b128 v[172:175], v155 offset:36864
	ds_read_b128 v[176:179], v155 offset:37888
	ds_read_b128 v[204:207], v155 offset:38912
	ds_read_b128 v[208:211], v155 offset:39936
	global_load_lds_dwordx4 v[212:213], off
	v_lshl_add_u64 v[212:213], s[26:27], 0, v[128:129]
	s_mov_b32 m0, s45
	s_nop 0
	global_load_lds_dwordx4 v[212:213], off
	s_waitcnt lgkmcnt(8)
	s_barrier
	s_waitcnt lgkmcnt(0)
	s_setprio 1
	s_waitcnt lgkmcnt(0)
	v_mfma_f32_16x16x32_bf16 v[124:127], v[134:137], v[156:159], v[124:127]
	v_mfma_f32_16x16x32_bf16 v[120:123], v[142:145], v[156:159], v[120:123]
	v_mfma_f32_16x16x32_bf16 v[108:111], v[134:137], v[164:167], v[108:111]
	v_mfma_f32_16x16x32_bf16 v[104:107], v[142:145], v[164:167], v[104:107]
	v_mfma_f32_16x16x32_bf16 v[92:95], v[134:137], v[172:175], v[92:95]
	v_mfma_f32_16x16x32_bf16 v[88:91], v[142:145], v[172:175], v[88:91]
	v_mfma_f32_16x16x32_bf16 v[76:79], v[134:137], v[204:207], v[76:79]
	v_mfma_f32_16x16x32_bf16 v[72:75], v[142:145], v[204:207], v[72:75]
	v_mfma_f32_16x16x32_bf16 v[124:127], v[138:141], v[160:163], v[124:127]
	v_mfma_f32_16x16x32_bf16 v[120:123], v[146:149], v[160:163], v[120:123]
	v_mfma_f32_16x16x32_bf16 v[108:111], v[138:141], v[168:171], v[108:111]
	v_mfma_f32_16x16x32_bf16 v[104:107], v[146:149], v[168:171], v[104:107]
	v_mfma_f32_16x16x32_bf16 v[92:95], v[138:141], v[176:179], v[92:95]
	v_mfma_f32_16x16x32_bf16 v[88:91], v[146:149], v[176:179], v[88:91]
	v_mfma_f32_16x16x32_bf16 v[76:79], v[138:141], v[208:211], v[76:79]
	v_mfma_f32_16x16x32_bf16 v[72:75], v[146:149], v[208:211], v[72:75]
	s_setprio 0
	s_barrier
	s_add_i32 s30, 0, 0x1c000
	s_add_i32 s26, s58, s41
	v_add_u32_e32 v191, s30, v153
	v_lshl_add_u64 v[150:151], v[150:151], 0, s[0:1]
	s_mov_b32 m0, s26
	ds_read_b128 v[212:215], v191
	ds_read_b128 v[216:219], v191 offset:1024
	ds_read_b128 v[220:223], v191 offset:2048
	ds_read_b128 v[224:227], v191 offset:3072
	global_load_lds_dwordx4 v[150:151], off
	v_lshl_add_u64 v[150:151], v[198:199], 0, s[0:1]
	s_add_i32 m0, s26, 0x2000
	s_nop 0
	global_load_lds_dwordx4 v[150:151], off
	s_barrier
; #define PG8_STAGE(bufoff, gbase, voff) do { _Pragma("unroll") for (int _i = 0; _i < 2; ++_i) \
;         __builtin_amdgcn_global_load_lds((const unsigned*)((const char*)(gbase) + (voff)[_i]), (LAS unsigned*)(lds + (bufoff) + ldsw + _i * 8192), 16, 0, 0); } while (0)
; #define PG8_LDA(dst, b, h) do { _Pragma("unroll") for (int m = 0; m < 4; ++m) _Pragma("unroll") for (int k = 0; k < 2; ++k) dst[m][k] = *(const LAS bf16x8*)(lds + PG8_SA(b, h) + aoff + m * 2048 + k * 1024); } while (0)
; #define PG8_LDB(dst, b, h) do { _Pragma("unroll") for (int n = 0; n < 2; ++n) _Pragma("unroll") for (int k = 0; k < 2; ++k) dst[n][k] = *(const LAS bf16x8*)(lds + PG8_SB(b, h) + boff + n * 2048 + k * 1024); } while (0)
; #define PG8_MMA(ai, bj, At, Bt) do { __builtin_amdgcn_s_setprio(1); _Pragma("unroll") for (int m = 0; m < 4; ++m) _Pragma("unroll") for (int n = 0; n < 2; ++n) _Pragma("unroll") for (int k = 0; k < 2; ++k) \
;         acc[ai][bj][m][n] = __builtin_amdgcn_mfma_f32_16x16x32_bf16(Bt[n][k], At[m][k], acc[ai][bj][m][n], 0, 0, 0); __builtin_amdgcn_s_setprio(0); } while (0)
; #define PG8_WAIT_V(n) asm volatile("s_waitcnt vmcnt(" #n ")" ::: "memory")
; #define PG8_WAIT_L(n) asm volatile("s_waitcnt lgkmcnt(" #n ")" ::: "memory")
; template <class Epi>
; __device__ __forceinline__ void gemm_phase(const Tb tb, LAS unsigned char* lds, const Gemm g, const StaticOrder& S, const Epi& E) {
;     ...
;             PG8_WAIT_V(6); PG8_BAR; PG8_MMA(1, 1, At, B1); PG8_BAR;
;             PG8_LDB(B0, 1, 0); PG8_SCHED; PG8_LDA(At, 1, 0); PG8_STAGE(PG8_SA(0, 1), a2 + hstep, voffA);
;             PG8_WAIT_L(8); PG8_BAR; PG8_WAIT_L(0); PG8_MMA(0, 0, At, B0); PG8_BAR; PG8_SCHED;
;             PG8_LDB(B1, 1, 1); PG8_STAGE(PG8_SB(1, 0), b3, voffB);
;             PG8_BAR; PG8_WAIT_L(0); PG8_MMA(0, 1, At, B1); PG8_BAR;
;             PG8_LDA(At, 1, 1); PG8_STAGE(PG8_SA(1, 0), a3, voffA);
;             PG8_BAR; PG8_WAIT_L(0); PG8_MMA(1, 0, At, B0); PG8_BAR; PG8_SCHED;
;             PG8_STAGE(PG8_SB(1, 1), b3 + hstep, voffB);
;             PG8_WAIT_V(6); PG8_BAR; PG8_MMA(1, 1, At, B1); PG8_BAR;
;     __device__ __forceinline__ void operator()(const f32x4 (&acc)[2][2][4][2], const pg8::Unit& u, int wr, int wc, int fr, int fq) const {
;     ...
;             for (int m = 0; m < 4; ++m) {
;                 const int row = row0 + ai * 128 + m * 16; float mu, rstd; row_stats(stats_prev, row, mu, rstd);
	s_waitcnt lgkmcnt(0)
	s_setprio 1
	s_waitcnt lgkmcnt(0)
	v_mfma_f32_16x16x32_bf16 v[116:119], v[212:215], v[156:159], v[116:119]
	v_mfma_f32_16x16x32_bf16 v[112:115], v[220:223], v[156:159], v[112:115]
	v_mfma_f32_16x16x32_bf16 v[100:103], v[212:215], v[164:167], v[100:103]
	v_mfma_f32_16x16x32_bf16 v[96:99], v[220:223], v[164:167], v[96:99]
	v_mfma_f32_16x16x32_bf16 v[84:87], v[212:215], v[172:175], v[84:87]
	v_mfma_f32_16x16x32_bf16 v[80:83], v[220:223], v[172:175], v[80:83]
	v_mfma_f32_16x16x32_bf16 v[68:71], v[212:215], v[204:207], v[68:71]
	v_mfma_f32_16x16x32_bf16 v[64:67], v[220:223], v[204:207], v[64:67]
	v_mfma_f32_16x16x32_bf16 v[116:119], v[216:219], v[160:163], v[116:119]
	v_mfma_f32_16x16x32_bf16 v[112:115], v[224:227], v[160:163], v[112:115]
	v_mfma_f32_16x16x32_bf16 v[100:103], v[216:219], v[168:171], v[100:103]
	v_mfma_f32_16x16x32_bf16 v[96:99], v[224:227], v[168:171], v[96:99]
	v_mfma_f32_16x16x32_bf16 v[84:87], v[216:219], v[176:179], v[84:87]
	v_mfma_f32_16x16x32_bf16 v[80:83], v[224:227], v[176:179], v[80:83]
	v_mfma_f32_16x16x32_bf16 v[68:71], v[216:219], v[208:211], v[68:71]
	v_mfma_f32_16x16x32_bf16 v[64:67], v[224:227], v[208:211], v[64:67]
	s_setprio 0
	s_mov_b32 m0, s46
	v_lshl_add_u64 v[150:151], v[228:229], 0, s[0:1]
	s_barrier
	ds_read_b128 v[156:159], v155 offset:49152
	ds_read_b128 v[160:163], v155 offset:50176
	ds_read_b128 v[164:167], v155 offset:51200
	ds_read_b128 v[168:171], v155 offset:52224
	ds_read_b128 v[172:175], v155 offset:53248
	ds_read_b128 v[176:179], v155 offset:54272
	ds_read_b128 v[204:207], v155 offset:55296
	ds_read_b128 v[208:211], v155 offset:56320
	global_load_lds_dwordx4 v[150:151], off
	v_lshl_add_u64 v[150:151], v[230:231], 0, s[0:1]
	s_mov_b32 m0, s47
	s_nop 0
	global_load_lds_dwordx4 v[150:151], off
	s_barrier
	s_waitcnt lgkmcnt(0)
	s_setprio 1
	s_waitcnt lgkmcnt(0)
	v_mfma_f32_16x16x32_bf16 v[60:63], v[134:137], v[156:159], v[60:63]
	v_mfma_f32_16x16x32_bf16 v[56:59], v[142:145], v[156:159], v[56:59]
	v_mfma_f32_16x16x32_bf16 v[44:47], v[134:137], v[164:167], v[44:47]
	v_mfma_f32_16x16x32_bf16 v[40:43], v[142:145], v[164:167], v[40:43]
	v_mfma_f32_16x16x32_bf16 v[28:31], v[134:137], v[172:175], v[28:31]
	v_mfma_f32_16x16x32_bf16 v[24:27], v[142:145], v[172:175], v[24:27]
	v_mfma_f32_16x16x32_bf16 v[12:15], v[134:137], v[204:207], v[12:15]
	v_mfma_f32_16x16x32_bf16 v[8:11], v[142:145], v[204:207], v[8:11]
	v_mfma_f32_16x16x32_bf16 v[60:63], v[138:141], v[160:163], v[60:63]
	v_mfma_f32_16x16x32_bf16 v[56:59], v[146:149], v[160:163], v[56:59]
	v_mfma_f32_16x16x32_bf16 v[44:47], v[138:141], v[168:171], v[44:47]
	v_mfma_f32_16x16x32_bf16 v[40:43], v[146:149], v[168:171], v[40:43]
	v_mfma_f32_16x16x32_bf16 v[28:31], v[138:141], v[176:179], v[28:31]
	v_mfma_f32_16x16x32_bf16 v[24:27], v[146:149], v[176:179], v[24:27]
	v_mfma_f32_16x16x32_bf16 v[12:15], v[138:141], v[208:211], v[12:15]
	v_mfma_f32_16x16x32_bf16 v[8:11], v[146:149], v[208:211], v[8:11]
	s_setprio 0
	s_barrier
	s_add_u32 s26, s28, 0xb0080
	s_addc_u32 s27, s29, 0
	s_add_i32 s28, s30, s41
	v_lshl_add_u64 v[134:135], s[26:27], 0, v[180:181]
	s_mov_b32 m0, s28
	s_nop 0
	global_load_lds_dwordx4 v[134:135], off
	v_lshl_add_u64 v[134:135], s[26:27], 0, v[128:129]
	s_add_i32 m0, s28, 0x2000
	s_nop 0
	global_load_lds_dwordx4 v[134:135], off
	s_waitcnt vmcnt(6)
	s_barrier
	s_setprio 1
	v_mfma_f32_16x16x32_bf16 v[52:55], v[212:215], v[156:159], v[52:55]
	v_mfma_f32_16x16x32_bf16 v[48:51], v[220:223], v[156:159], v[48:51]
	v_mfma_f32_16x16x32_bf16 v[36:39], v[212:215], v[164:167], v[36:39]
	v_mfma_f32_16x16x32_bf16 v[32:35], v[220:223], v[164:167], v[32:35]
	v_mfma_f32_16x16x32_bf16 v[20:23], v[212:215], v[172:175], v[20:23]
	v_mfma_f32_16x16x32_bf16 v[16:19], v[220:223], v[172:175], v[16:19]
	v_mfma_f32_16x16x32_bf16 v[4:7], v[212:215], v[204:207], v[4:7]
	v_mfma_f32_16x16x32_bf16 v[0:3], v[220:223], v[204:207], v[0:3]
	v_mfma_f32_16x16x32_bf16 v[52:55], v[216:219], v[160:163], v[52:55]
	v_mfma_f32_16x16x32_bf16 v[48:51], v[224:227], v[160:163], v[48:51]
	v_mfma_f32_16x16x32_bf16 v[36:39], v[216:219], v[168:171], v[36:39]
	v_mfma_f32_16x16x32_bf16 v[32:35], v[224:227], v[168:171], v[32:35]
	v_mfma_f32_16x16x32_bf16 v[20:23], v[216:219], v[176:179], v[20:23]
	v_mfma_f32_16x16x32_bf16 v[16:19], v[224:227], v[176:179], v[16:19]
	v_mfma_f32_16x16x32_bf16 v[4:7], v[216:219], v[208:211], v[4:7]
	v_mfma_f32_16x16x32_bf16 v[0:3], v[224:227], v[208:211], v[0:3]
	s_setprio 0
	s_add_i32 s57, s57, 2
	s_add_u32 s55, s55, 0x100
	s_addc_u32 s56, s56, 0
	s_cmp_gt_u32 s57, 41
	s_mov_b64 s[26:27], s[6:7]
	s_barrier
	s_cbranch_scc0 .LBB0_65
	v_lshl_add_u32 v138, s54, 8, v152
	v_cndmask_b32_e64 v134, 0, 1, s[22:23]
	v_cmp_ne_u32_e64 s[6:7], 1, v134
	s_andn2_b64 vcc, exec, s[22:23]
	v_ashrrev_i32_e32 v139, 31, v138
	s_cbranch_vccnz .LBB0_68
	v_lshl_add_u64 v[134:135], v[138:139], 3, s[12:13]
	global_load_dwordx2 v[144:145], v[134:135], off
	global_load_dwordx2 v[226:227], v[134:135], off offset:128
	global_load_dwordx2 v[232:233], v[134:135], off offset:256
	global_load_dwordx2 v[234:235], v[134:135], off offset:384
	global_load_dwordx2 v[242:243], v[134:135], off offset:1024
	global_load_dwordx2 v[244:245], v[134:135], off offset:1152
	global_load_dwordx2 v[250:251], v[134:135], off offset:1280
	s_waitcnt vmcnt(0)
	v_mov_b32_e32 v146, v145
	s_branch .LBB0_69

; __device__ __forceinline__ void row_stats(const float* mur, int row, float& mu, float& rstd) {
;     if (mur) { const float2 v = *(const float2*)(mur + 2 * (size_t)row); mu = v.x; rstd = v.y; }
;     else { mu = 0.f; rstd = 1.f; }
;     __device__ __forceinline__ void operator()(const f32x4 (&acc)[2][2][4][2], const pg8::Unit& u, int wr, int wc, int fr, int fq) const {
;     ...
;             for (int m = 0; m < 4; ++m) {
;                 const int row = row0 + ai * 128 + m * 16; float mu, rstd; row_stats(stats_prev, row, mu, rstd);
.LBB0_79:
	s_or_b64 exec, exec, s[28:29]
	v_or_b32_e32 v112, 16, v138
	s_and_b64 vcc, exec, s[6:7]
	v_ashrrev_i32_e32 v113, 31, v112
	s_cbranch_vccnz .LBB0_81
	s_waitcnt lgkmcnt(0)
	v_mov_b32_e32 v116, v226
	v_mov_b32_e32 v117, v227
	v_mov_b32_e32 v118, v117
	s_branch .LBB0_82

; __device__ __forceinline__ void row_stats(const float* mur, int row, float& mu, float& rstd) {
;     if (mur) { const float2 v = *(const float2*)(mur + 2 * (size_t)row); mu = v.x; rstd = v.y; }
;     else { mu = 0.f; rstd = 1.f; }
;     __device__ __forceinline__ void operator()(const f32x4 (&acc)[2][2][4][2], const pg8::Unit& u, int wr, int wc, int fr, int fq) const {
;     ...
;             for (int m = 0; m < 4; ++m) {
;                 const int row = row0 + ai * 128 + m * 16; float mu, rstd; row_stats(stats_prev, row, mu, rstd);
.LBB0_92:
	s_or_b64 exec, exec, s[28:29]
	v_or_b32_e32 v96, 32, v138
	s_and_b64 vcc, exec, s[6:7]
	v_ashrrev_i32_e32 v97, 31, v96
	s_cbranch_vccnz .LBB0_94
	s_waitcnt lgkmcnt(0)
	v_mov_b32_e32 v100, v232
	v_mov_b32_e32 v101, v233
	v_mov_b32_e32 v102, v101
	s_branch .LBB0_95

; __device__ __forceinline__ void row_stats(const float* mur, int row, float& mu, float& rstd) {
;     if (mur) { const float2 v = *(const float2*)(mur + 2 * (size_t)row); mu = v.x; rstd = v.y; }
;     else { mu = 0.f; rstd = 1.f; }
;     __device__ __forceinline__ void operator()(const f32x4 (&acc)[2][2][4][2], const pg8::Unit& u, int wr, int wc, int fr, int fq) const {
;     ...
;             for (int m = 0; m < 4; ++m) {
;                 const int row = row0 + ai * 128 + m * 16; float mu, rstd; row_stats(stats_prev, row, mu, rstd);
.LBB0_105:
	s_or_b64 exec, exec, s[28:29]
	v_or_b32_e32 v80, 48, v138
	s_and_b64 vcc, exec, s[6:7]
	v_ashrrev_i32_e32 v81, 31, v80
	s_cbranch_vccnz .LBB0_107
	s_waitcnt lgkmcnt(0)
	v_mov_b32_e32 v84, v234
	v_mov_b32_e32 v85, v235
	v_mov_b32_e32 v86, v85
	s_branch .LBB0_108

; __device__ __forceinline__ void row_stats(const float* mur, int row, float& mu, float& rstd) {
;     if (mur) { const float2 v = *(const float2*)(mur + 2 * (size_t)row); mu = v.x; rstd = v.y; }
;     else { mu = 0.f; rstd = 1.f; }
;     __device__ __forceinline__ void operator()(const f32x4 (&acc)[2][2][4][2], const pg8::Unit& u, int wr, int wc, int fr, int fq) const {
;     ...
;             for (int m = 0; m < 4; ++m) {
;                 const int row = row0 + ai * 128 + m * 16; float mu, rstd; row_stats(stats_prev, row, mu, rstd);
.LBB0_118:
	s_or_b64 exec, exec, s[28:29]
	v_add_u32_e32 v64, 0x80, v138
	s_and_b64 vcc, exec, s[6:7]
	v_ashrrev_i32_e32 v65, 31, v64
	s_cbranch_vccnz .LBB0_120
	s_waitcnt lgkmcnt(0)
	v_mov_b32_e32 v68, v242
	v_mov_b32_e32 v69, v243
	v_mov_b32_e32 v70, v69
	s_branch .LBB0_121

; __device__ __forceinline__ void row_stats(const float* mur, int row, float& mu, float& rstd) {
;     if (mur) { const float2 v = *(const float2*)(mur + 2 * (size_t)row); mu = v.x; rstd = v.y; }
;     else { mu = 0.f; rstd = 1.f; }
;     __device__ __forceinline__ void operator()(const f32x4 (&acc)[2][2][4][2], const pg8::Unit& u, int wr, int wc, int fr, int fq) const {
;     ...
;             for (int m = 0; m < 4; ++m) {
;                 const int row = row0 + ai * 128 + m * 16; float mu, rstd; row_stats(stats_prev, row, mu, rstd);
.LBB0_131:
	s_or_b64 exec, exec, s[28:29]
	v_add_u32_e32 v48, 0x90, v138
	s_and_b64 vcc, exec, s[6:7]
	v_ashrrev_i32_e32 v49, 31, v48
	s_cbranch_vccnz .LBB0_133
	s_waitcnt lgkmcnt(0)
	v_mov_b32_e32 v52, v244
	v_mov_b32_e32 v53, v245
	v_mov_b32_e32 v54, v53
	s_branch .LBB0_134

; __device__ __forceinline__ void row_stats(const float* mur, int row, float& mu, float& rstd) {
;     if (mur) { const float2 v = *(const float2*)(mur + 2 * (size_t)row); mu = v.x; rstd = v.y; }
;     else { mu = 0.f; rstd = 1.f; }
;     __device__ __forceinline__ void operator()(const f32x4 (&acc)[2][2][4][2], const pg8::Unit& u, int wr, int wc, int fr, int fq) const {
;     ...
;             for (int m = 0; m < 4; ++m) {
;                 const int row = row0 + ai * 128 + m * 16; float mu, rstd; row_stats(stats_prev, row, mu, rstd);
.LBB0_144:
	s_or_b64 exec, exec, s[28:29]
	v_add_u32_e32 v32, 0xa0, v138
	s_and_b64 vcc, exec, s[6:7]
	v_ashrrev_i32_e32 v33, 31, v32
	s_cbranch_vccnz .LBB0_146
	s_waitcnt lgkmcnt(0)
	v_mov_b32_e32 v36, v250
	v_mov_b32_e32 v37, v251
	v_mov_b32_e32 v38, v37
	s_branch .LBB0_147

; #define PG8_STAGE(bufoff, gbase, voff) do { _Pragma("unroll") for (int _i = 0; _i < 2; ++_i) \
;         __builtin_amdgcn_global_load_lds((const unsigned*)((const char*)(gbase) + (voff)[_i]), (LAS unsigned*)(lds + (bufoff) + ldsw + _i * 8192), 16, 0, 0); } while (0)
; #define PG8_LDA(dst, b, h) do { _Pragma("unroll") for (int m = 0; m < 4; ++m) _Pragma("unroll") for (int k = 0; k < 2; ++k) dst[m][k] = *(const LAS bf16x8*)(lds + PG8_SA(b, h) + aoff + m * 2048 + k * 1024); } while (0)
; #define PG8_LDB(dst, b, h) do { _Pragma("unroll") for (int n = 0; n < 2; ++n) _Pragma("unroll") for (int k = 0; k < 2; ++k) dst[n][k] = *(const LAS bf16x8*)(lds + PG8_SB(b, h) + boff + n * 2048 + k * 1024); } while (0)
; #define PG8_MMA(ai, bj, At, Bt) do { __builtin_amdgcn_s_setprio(1); _Pragma("unroll") for (int m = 0; m < 4; ++m) _Pragma("unroll") for (int n = 0; n < 2; ++n) _Pragma("unroll") for (int k = 0; k < 2; ++k) \
;         acc[ai][bj][m][n] = __builtin_amdgcn_mfma_f32_16x16x32_bf16(Bt[n][k], At[m][k], acc[ai][bj][m][n], 0, 0, 0); __builtin_amdgcn_s_setprio(0); } while (0)
; #define PG8_WAIT_V(n) asm volatile("s_waitcnt vmcnt(" #n ")" ::: "memory")
; #define PG8_WAIT_L(n) asm volatile("s_waitcnt lgkmcnt(" #n ")" ::: "memory")
; template <class Epi>
; __device__ __forceinline__ void gemm_phase(const Tb tb, LAS unsigned char* lds, const Gemm g, const StaticOrder& S, const Epi& E) {
;     ...
;         for (int t = 0; t < nt; t += 2) {
;             const bool last = (t == nt - 2);
;             const char* a1 = cA + (size_t)(t + 1) * kstep;
;             const char* a2 = last ? nA : cA + (size_t)(t + 2) * kstep; const char* b2 = last ? nB : cB + (size_t)(t + 2) * kstep;
;             const char* a3 = a2 + kstep; const char* b3 = b2 + kstep;
;             PG8_LDB(B0, 0, 0); PG8_SCHED; PG8_LDA(At, 0, 0); PG8_STAGE(PG8_SA(1, 1), a1 + hstep, voffA);
;             PG8_WAIT_L(8); PG8_BAR; PG8_WAIT_L(0); PG8_MMA(0, 0, At, B0); PG8_BAR; PG8_SCHED;
;             PG8_LDB(B1, 0, 1); PG8_STAGE(PG8_SB(0, 0), b2, voffB);
;             PG8_BAR; PG8_WAIT_L(0); PG8_MMA(0, 1, At, B1); PG8_BAR;
;             PG8_LDA(At, 0, 1); PG8_STAGE(PG8_SA(0, 0), a2, voffA);
;             PG8_BAR; PG8_WAIT_L(0); PG8_MMA(1, 0, At, B0); PG8_BAR; PG8_SCHED;
;             PG8_STAGE(PG8_SB(0, 1), b2 + hstep, voffB);
;             PG8_WAIT_V(6); PG8_BAR; PG8_MMA(1, 1, At, B1); PG8_BAR;
.LBB0_234:
	s_add_u32 s30, s28, 0x100
	s_addc_u32 s31, s29, 0
	s_add_i32 s58, 0, 0x10000
	v_add_u32_e32 v146, s58, v153
	ds_read_b128 v[134:137], v146
	ds_read_b128 v[138:141], v146 offset:1024
	ds_read_b128 v[142:145], v146 offset:2048
	ds_read_b128 v[146:149], v146 offset:3072
	s_cmp_eq_u32 s57, 12
	s_cselect_b32 s37, s7, s31
	s_cselect_b32 s36, s21, s30
	s_cselect_b32 s35, s19, s56
	s_cselect_b32 s34, s27, s55
	v_lshl_add_u64 v[150:151], s[28:29], 0, v[132:133]
	s_add_i32 m0, s45, 0xc000
	ds_read_b128 v[156:159], v155
	ds_read_b128 v[160:163], v155 offset:1024
	ds_read_b128 v[164:167], v155 offset:2048
	ds_read_b128 v[168:171], v155 offset:3072
	ds_read_b128 v[172:175], v155 offset:4096
	ds_read_b128 v[176:179], v155 offset:5120
	ds_read_b128 v[204:207], v155 offset:6144
	ds_read_b128 v[208:211], v155 offset:7168
	global_load_lds_dwordx4 v[150:151], off
	v_lshl_add_u64 v[150:151], s[28:29], 0, v[130:131]
	s_add_i32 m0, s45, 0xe000
	s_nop 0
	global_load_lds_dwordx4 v[150:151], off
	s_waitcnt lgkmcnt(8)
	s_barrier
	s_waitcnt lgkmcnt(0)
	s_setprio 1
	s_waitcnt lgkmcnt(0)
	v_mfma_f32_16x16x32_bf16 v[124:127], v[134:137], v[156:159], v[124:127]
	v_mfma_f32_16x16x32_bf16 v[120:123], v[142:145], v[156:159], v[120:123]
	v_mfma_f32_16x16x32_bf16 v[108:111], v[134:137], v[164:167], v[108:111]
	v_mfma_f32_16x16x32_bf16 v[104:107], v[142:145], v[164:167], v[104:107]
	v_mfma_f32_16x16x32_bf16 v[92:95], v[134:137], v[172:175], v[92:95]
	v_mfma_f32_16x16x32_bf16 v[88:91], v[142:145], v[172:175], v[88:91]
	v_mfma_f32_16x16x32_bf16 v[76:79], v[134:137], v[204:207], v[76:79]
	v_mfma_f32_16x16x32_bf16 v[72:75], v[142:145], v[204:207], v[72:75]
	v_mfma_f32_16x16x32_bf16 v[124:127], v[138:141], v[160:163], v[124:127]
	v_mfma_f32_16x16x32_bf16 v[120:123], v[146:149], v[160:163], v[120:123]
	v_mfma_f32_16x16x32_bf16 v[108:111], v[138:141], v[168:171], v[108:111]
	v_mfma_f32_16x16x32_bf16 v[104:107], v[146:149], v[168:171], v[104:107]
	v_mfma_f32_16x16x32_bf16 v[92:95], v[138:141], v[176:179], v[92:95]
	v_mfma_f32_16x16x32_bf16 v[88:91], v[146:149], v[176:179], v[88:91]
	v_mfma_f32_16x16x32_bf16 v[76:79], v[138:141], v[208:211], v[76:79]
	v_mfma_f32_16x16x32_bf16 v[72:75], v[146:149], v[208:211], v[72:75]
	s_setprio 0
	s_barrier
	s_add_i32 s59, 0, 0x14000
	v_add_u32_e32 v150, s59, v153
	s_add_i32 s28, s58, s44
	ds_read_b128 v[212:215], v150
	ds_read_b128 v[216:219], v150 offset:1024
	ds_read_b128 v[220:223], v150 offset:2048
	ds_read_b128 v[224:227], v150 offset:3072
	v_lshl_add_u64 v[150:151], s[34:35], 0, v[180:181]
	s_mov_b32 m0, s28
	v_lshl_add_u64 v[198:199], s[34:35], 0, v[128:129]
	global_load_lds_dwordx4 v[150:151], off
	s_add_i32 m0, s28, 0x2000
	s_nop 0
	global_load_lds_dwordx4 v[198:199], off
	s_barrier
	s_waitcnt lgkmcnt(0)
	s_setprio 1
	s_waitcnt lgkmcnt(0)
	v_mfma_f32_16x16x32_bf16 v[116:119], v[212:215], v[156:159], v[116:119]
	v_mfma_f32_16x16x32_bf16 v[112:115], v[220:223], v[156:159], v[112:115]
	v_mfma_f32_16x16x32_bf16 v[100:103], v[212:215], v[164:167], v[100:103]
	v_mfma_f32_16x16x32_bf16 v[96:99], v[220:223], v[164:167], v[96:99]
	v_mfma_f32_16x16x32_bf16 v[84:87], v[212:215], v[172:175], v[84:87]
	v_mfma_f32_16x16x32_bf16 v[80:83], v[220:223], v[172:175], v[80:83]
	v_mfma_f32_16x16x32_bf16 v[68:71], v[212:215], v[204:207], v[68:71]
	v_mfma_f32_16x16x32_bf16 v[64:67], v[220:223], v[204:207], v[64:67]
	v_mfma_f32_16x16x32_bf16 v[116:119], v[216:219], v[160:163], v[116:119]
	v_mfma_f32_16x16x32_bf16 v[112:115], v[224:227], v[160:163], v[112:115]
	v_mfma_f32_16x16x32_bf16 v[100:103], v[216:219], v[168:171], v[100:103]
	v_mfma_f32_16x16x32_bf16 v[96:99], v[224:227], v[168:171], v[96:99]
	v_mfma_f32_16x16x32_bf16 v[84:87], v[216:219], v[176:179], v[84:87]
	v_mfma_f32_16x16x32_bf16 v[80:83], v[224:227], v[176:179], v[80:83]
	v_mfma_f32_16x16x32_bf16 v[68:71], v[216:219], v[208:211], v[68:71]
	v_mfma_f32_16x16x32_bf16 v[64:67], v[224:227], v[208:211], v[64:67]
	s_setprio 0
	s_mov_b32 m0, s45
	v_lshl_add_u64 v[228:229], s[36:37], 0, v[180:181]
	s_barrier
	ds_read_b128 v[156:159], v155 offset:16384
	ds_read_b128 v[160:163], v155 offset:17408
	ds_read_b128 v[164:167], v155 offset:18432
	ds_read_b128 v[168:171], v155 offset:19456
	ds_read_b128 v[172:175], v155 offset:20480
	ds_read_b128 v[176:179], v155 offset:21504
	ds_read_b128 v[204:207], v155 offset:22528
	ds_read_b128 v[208:211], v155 offset:23552
	global_load_lds_dwordx4 v[228:229], off
	v_lshl_add_u64 v[230:231], s[36:37], 0, v[128:129]
	s_mov_b32 m0, s46
	s_nop 0
	global_load_lds_dwordx4 v[230:231], off
	s_barrier
	s_waitcnt lgkmcnt(0)
	s_setprio 1
	s_waitcnt lgkmcnt(0)
	v_mfma_f32_16x16x32_bf16 v[60:63], v[134:137], v[156:159], v[60:63]
	v_mfma_f32_16x16x32_bf16 v[56:59], v[142:145], v[156:159], v[56:59]
	v_mfma_f32_16x16x32_bf16 v[44:47], v[134:137], v[164:167], v[44:47]
	v_mfma_f32_16x16x32_bf16 v[40:43], v[142:145], v[164:167], v[40:43]
	v_mfma_f32_16x16x32_bf16 v[28:31], v[134:137], v[172:175], v[28:31]
	v_mfma_f32_16x16x32_bf16 v[24:27], v[142:145], v[172:175], v[24:27]
	v_mfma_f32_16x16x32_bf16 v[12:15], v[134:137], v[204:207], v[12:15]
	v_mfma_f32_16x16x32_bf16 v[8:11], v[142:145], v[204:207], v[8:11]
	v_mfma_f32_16x16x32_bf16 v[60:63], v[138:141], v[160:163], v[60:63]
	v_mfma_f32_16x16x32_bf16 v[56:59], v[146:149], v[160:163], v[56:59]
	v_mfma_f32_16x16x32_bf16 v[44:47], v[138:141], v[168:171], v[44:47]
	v_mfma_f32_16x16x32_bf16 v[40:43], v[146:149], v[168:171], v[40:43]
	v_mfma_f32_16x16x32_bf16 v[28:31], v[138:141], v[176:179], v[28:31]
	v_mfma_f32_16x16x32_bf16 v[24:27], v[146:149], v[176:179], v[24:27]
	v_mfma_f32_16x16x32_bf16 v[12:15], v[138:141], v[208:211], v[12:15]
	v_mfma_f32_16x16x32_bf16 v[8:11], v[146:149], v[208:211], v[8:11]
	s_setprio 0
	s_barrier
; #define PG8_STAGE(bufoff, gbase, voff) do { _Pragma("unroll") for (int _i = 0; _i < 2; ++_i) \
;         __builtin_amdgcn_global_load_lds((const unsigned*)((const char*)(gbase) + (voff)[_i]), (LAS unsigned*)(lds + (bufoff) + ldsw + _i * 8192), 16, 0, 0); } while (0)
; #define PG8_LDA(dst, b, h) do { _Pragma("unroll") for (int m = 0; m < 4; ++m) _Pragma("unroll") for (int k = 0; k < 2; ++k) dst[m][k] = *(const LAS bf16x8*)(lds + PG8_SA(b, h) + aoff + m * 2048 + k * 1024); } while (0)
; #define PG8_LDB(dst, b, h) do { _Pragma("unroll") for (int n = 0; n < 2; ++n) _Pragma("unroll") for (int k = 0; k < 2; ++k) dst[n][k] = *(const LAS bf16x8*)(lds + PG8_SB(b, h) + boff + n * 2048 + k * 1024); } while (0)
; #define PG8_MMA(ai, bj, At, Bt) do { __builtin_amdgcn_s_setprio(1); _Pragma("unroll") for (int m = 0; m < 4; ++m) _Pragma("unroll") for (int n = 0; n < 2; ++n) _Pragma("unroll") for (int k = 0; k < 2; ++k) \
;         acc[ai][bj][m][n] = __builtin_amdgcn_mfma_f32_16x16x32_bf16(Bt[n][k], At[m][k], acc[ai][bj][m][n], 0, 0, 0); __builtin_amdgcn_s_setprio(0); } while (0)
; #define PG8_WAIT_V(n) asm volatile("s_waitcnt vmcnt(" #n ")" ::: "memory")
; #define PG8_WAIT_L(n) asm volatile("s_waitcnt lgkmcnt(" #n ")" ::: "memory")
; #define PG8_BAR __builtin_amdgcn_s_barrier()
; #define PG8_SCHED __builtin_amdgcn_sched_barrier(0)
; template <class Epi>
; __device__ __forceinline__ void gemm_phase(const Tb tb, LAS unsigned char* lds, const Gemm g, const StaticOrder& S, const Epi& E) {
;     ...
;             PG8_WAIT_V(6); PG8_BAR; PG8_MMA(1, 1, At, B1); PG8_BAR;
;             PG8_LDB(B0, 1, 0); PG8_SCHED; PG8_LDA(At, 1, 0); PG8_STAGE(PG8_SA(0, 1), a2 + hstep, voffA);
;             PG8_WAIT_L(8); PG8_BAR; PG8_WAIT_L(0); PG8_MMA(0, 0, At, B0); PG8_BAR; PG8_SCHED;
;             PG8_LDB(B1, 1, 1); PG8_STAGE(PG8_SB(1, 0), b3, voffB);
;             PG8_BAR; PG8_WAIT_L(0); PG8_MMA(0, 1, At, B1); PG8_BAR;
;             PG8_LDA(At, 1, 1); PG8_STAGE(PG8_SA(1, 0), a3, voffA);
;             PG8_BAR; PG8_WAIT_L(0); PG8_MMA(1, 0, At, B0); PG8_BAR; PG8_SCHED;
	s_add_u32 s28, s34, 0x40000
	s_addc_u32 s29, s35, 0
	s_add_i32 s58, s59, s44
	v_lshl_add_u64 v[134:135], s[28:29], 0, v[180:181]
	s_mov_b32 m0, s58
	s_nop 0
	global_load_lds_dwordx4 v[134:135], off
	v_lshl_add_u64 v[134:135], s[28:29], 0, v[128:129]
	s_add_i32 m0, s58, 0x2000
	s_nop 0
	global_load_lds_dwordx4 v[134:135], off
	s_waitcnt vmcnt(6)
	s_barrier
	s_setprio 1
	v_mfma_f32_16x16x32_bf16 v[52:55], v[212:215], v[156:159], v[52:55]
	v_mfma_f32_16x16x32_bf16 v[48:51], v[220:223], v[156:159], v[48:51]
	v_mfma_f32_16x16x32_bf16 v[36:39], v[212:215], v[164:167], v[36:39]
	v_mfma_f32_16x16x32_bf16 v[32:35], v[220:223], v[164:167], v[32:35]
	v_mfma_f32_16x16x32_bf16 v[20:23], v[212:215], v[172:175], v[20:23]
	v_mfma_f32_16x16x32_bf16 v[16:19], v[220:223], v[172:175], v[16:19]
	v_mfma_f32_16x16x32_bf16 v[4:7], v[212:215], v[204:207], v[4:7]
	v_mfma_f32_16x16x32_bf16 v[0:3], v[220:223], v[204:207], v[0:3]
	v_mfma_f32_16x16x32_bf16 v[52:55], v[216:219], v[160:163], v[52:55]
	v_mfma_f32_16x16x32_bf16 v[48:51], v[224:227], v[160:163], v[48:51]
	v_mfma_f32_16x16x32_bf16 v[36:39], v[216:219], v[168:171], v[36:39]
	v_mfma_f32_16x16x32_bf16 v[32:35], v[224:227], v[168:171], v[32:35]
	v_mfma_f32_16x16x32_bf16 v[20:23], v[216:219], v[176:179], v[20:23]
	v_mfma_f32_16x16x32_bf16 v[16:19], v[224:227], v[176:179], v[16:19]
	v_mfma_f32_16x16x32_bf16 v[4:7], v[216:219], v[208:211], v[4:7]
	v_mfma_f32_16x16x32_bf16 v[0:3], v[224:227], v[208:211], v[0:3]
	s_setprio 0
	s_add_i32 s58, 0, 0x18000
	v_add_u32_e32 v146, s58, v153
	s_barrier
	ds_read_b128 v[134:137], v146
	ds_read_b128 v[138:141], v146 offset:1024
	ds_read_b128 v[142:145], v146 offset:2048
	ds_read_b128 v[146:149], v146 offset:3072
	s_add_u32 s28, s36, 0x40000
	s_addc_u32 s29, s37, 0
	s_mov_b32 m0, s47
	v_lshl_add_u64 v[212:213], s[28:29], 0, v[180:181]
	ds_read_b128 v[156:159], v155 offset:32768
	ds_read_b128 v[160:163], v155 offset:33792
	ds_read_b128 v[164:167], v155 offset:34816
	ds_read_b128 v[168:171], v155 offset:35840
	ds_read_b128 v[172:175], v155 offset:36864
	ds_read_b128 v[176:179], v155 offset:37888
	ds_read_b128 v[204:207], v155 offset:38912
	ds_read_b128 v[208:211], v155 offset:39936
	global_load_lds_dwordx4 v[212:213], off
	v_lshl_add_u64 v[212:213], s[28:29], 0, v[128:129]
	s_mov_b32 m0, s48
	s_nop 0
	global_load_lds_dwordx4 v[212:213], off
	s_waitcnt lgkmcnt(8)
	s_barrier
	s_waitcnt lgkmcnt(0)
	s_setprio 1
	s_waitcnt lgkmcnt(0)
	v_mfma_f32_16x16x32_bf16 v[124:127], v[134:137], v[156:159], v[124:127]
	v_mfma_f32_16x16x32_bf16 v[120:123], v[142:145], v[156:159], v[120:123]
	v_mfma_f32_16x16x32_bf16 v[108:111], v[134:137], v[164:167], v[108:111]
	v_mfma_f32_16x16x32_bf16 v[104:107], v[142:145], v[164:167], v[104:107]
	v_mfma_f32_16x16x32_bf16 v[92:95], v[134:137], v[172:175], v[92:95]
	v_mfma_f32_16x16x32_bf16 v[88:91], v[142:145], v[172:175], v[88:91]
	v_mfma_f32_16x16x32_bf16 v[76:79], v[134:137], v[204:207], v[76:79]
	v_mfma_f32_16x16x32_bf16 v[72:75], v[142:145], v[204:207], v[72:75]
	v_mfma_f32_16x16x32_bf16 v[124:127], v[138:141], v[160:163], v[124:127]
	v_mfma_f32_16x16x32_bf16 v[120:123], v[146:149], v[160:163], v[120:123]
	v_mfma_f32_16x16x32_bf16 v[108:111], v[138:141], v[168:171], v[108:111]
	v_mfma_f32_16x16x32_bf16 v[104:107], v[146:149], v[168:171], v[104:107]
	v_mfma_f32_16x16x32_bf16 v[92:95], v[138:141], v[176:179], v[92:95]
	v_mfma_f32_16x16x32_bf16 v[88:91], v[146:149], v[176:179], v[88:91]
	v_mfma_f32_16x16x32_bf16 v[76:79], v[138:141], v[208:211], v[76:79]
	v_mfma_f32_16x16x32_bf16 v[72:75], v[146:149], v[208:211], v[72:75]
	s_setprio 0
	s_barrier
	s_add_i32 s36, 0, 0x1c000
	s_add_i32 s28, s58, s44
	v_add_u32_e32 v191, s36, v153
	v_lshl_add_u64 v[150:151], v[150:151], 0, s[0:1]
	s_mov_b32 m0, s28
	ds_read_b128 v[212:215], v191
	ds_read_b128 v[216:219], v191 offset:1024
	ds_read_b128 v[220:223], v191 offset:2048
	ds_read_b128 v[224:227], v191 offset:3072
	global_load_lds_dwordx4 v[150:151], off
	v_lshl_add_u64 v[150:151], v[198:199], 0, s[0:1]
	s_add_i32 m0, s28, 0x2000
	s_nop 0
	global_load_lds_dwordx4 v[150:151], off
	s_barrier
	s_waitcnt lgkmcnt(0)
	s_setprio 1
	s_waitcnt lgkmcnt(0)
	v_mfma_f32_16x16x32_bf16 v[116:119], v[212:215], v[156:159], v[116:119]
	v_mfma_f32_16x16x32_bf16 v[112:115], v[220:223], v[156:159], v[112:115]
	v_mfma_f32_16x16x32_bf16 v[100:103], v[212:215], v[164:167], v[100:103]
	v_mfma_f32_16x16x32_bf16 v[96:99], v[220:223], v[164:167], v[96:99]
	v_mfma_f32_16x16x32_bf16 v[84:87], v[212:215], v[172:175], v[84:87]
	v_mfma_f32_16x16x32_bf16 v[80:83], v[220:223], v[172:175], v[80:83]
	v_mfma_f32_16x16x32_bf16 v[68:71], v[212:215], v[204:207], v[68:71]
	v_mfma_f32_16x16x32_bf16 v[64:67], v[220:223], v[204:207], v[64:67]
	v_mfma_f32_16x16x32_bf16 v[116:119], v[216:219], v[160:163], v[116:119]
	v_mfma_f32_16x16x32_bf16 v[112:115], v[224:227], v[160:163], v[112:115]
	v_mfma_f32_16x16x32_bf16 v[100:103], v[216:219], v[168:171], v[100:103]
	v_mfma_f32_16x16x32_bf16 v[96:99], v[224:227], v[168:171], v[96:99]
	v_mfma_f32_16x16x32_bf16 v[84:87], v[216:219], v[176:179], v[84:87]
	v_mfma_f32_16x16x32_bf16 v[80:83], v[224:227], v[176:179], v[80:83]
	v_mfma_f32_16x16x32_bf16 v[68:71], v[216:219], v[208:211], v[68:71]
	v_mfma_f32_16x16x32_bf16 v[64:67], v[224:227], v[208:211], v[64:67]
	s_setprio 0
	s_mov_b32 m0, s49
	v_lshl_add_u64 v[150:151], v[228:229], 0, s[0:1]
	s_barrier
; #define PG8_STAGE(bufoff, gbase, voff) do { _Pragma("unroll") for (int _i = 0; _i < 2; ++_i) \
;         __builtin_amdgcn_global_load_lds((const unsigned*)((const char*)(gbase) + (voff)[_i]), (LAS unsigned*)(lds + (bufoff) + ldsw + _i * 8192), 16, 0, 0); } while (0)
; #define PG8_MMA(ai, bj, At, Bt) do { __builtin_amdgcn_s_setprio(1); _Pragma("unroll") for (int m = 0; m < 4; ++m) _Pragma("unroll") for (int n = 0; n < 2; ++n) _Pragma("unroll") for (int k = 0; k < 2; ++k) \
;         acc[ai][bj][m][n] = __builtin_amdgcn_mfma_f32_16x16x32_bf16(Bt[n][k], At[m][k], acc[ai][bj][m][n], 0, 0, 0); __builtin_amdgcn_s_setprio(0); } while (0)
; #define PG8_WAIT_V(n) asm volatile("s_waitcnt vmcnt(" #n ")" ::: "memory")
; #define PG8_WAIT_L(n) asm volatile("s_waitcnt lgkmcnt(" #n ")" ::: "memory")
; #define PG8_BAR __builtin_amdgcn_s_barrier()
; #define PG8_SCHED __builtin_amdgcn_sched_barrier(0)
; template <class Epi>
; __device__ __forceinline__ void gemm_phase(const Tb tb, LAS unsigned char* lds, const Gemm g, const StaticOrder& S, const Epi& E) {
;     ...
;             PG8_BAR; PG8_WAIT_L(0); PG8_MMA(1, 0, At, B0); PG8_BAR; PG8_SCHED;
;             PG8_STAGE(PG8_SB(1, 1), b3 + hstep, voffB);
;             PG8_WAIT_V(6); PG8_BAR; PG8_MMA(1, 1, At, B1); PG8_BAR;
;         }
;     __device__ __forceinline__ void operator()(const f32x4 (&acc)[2][2][4][2], const pg8::Unit& u, int wr, int wc, int fr, int fq) const {
;         const int row0 = u.pm * 256 + wr * 64 + fr, col0 = u.pn * 256 + wc * 32 + 4 * fq;
; #pragma unroll
;         for (int ai = 0; ai < 2; ++ai)
; #pragma unroll
;             for (int m = 0; m < 4; ++m) {
;                 const int row = row0 + ai * 128 + m * 16; float mu, rstd; row_stats(stats_prev, row, mu, rstd);
	ds_read_b128 v[156:159], v155 offset:49152
	ds_read_b128 v[160:163], v155 offset:50176
	ds_read_b128 v[164:167], v155 offset:51200
	ds_read_b128 v[168:171], v155 offset:52224
	ds_read_b128 v[172:175], v155 offset:53248
	ds_read_b128 v[176:179], v155 offset:54272
	ds_read_b128 v[204:207], v155 offset:55296
	ds_read_b128 v[208:211], v155 offset:56320
	global_load_lds_dwordx4 v[150:151], off
	v_lshl_add_u64 v[150:151], v[230:231], 0, s[0:1]
	s_mov_b32 m0, s50
	s_nop 0
	global_load_lds_dwordx4 v[150:151], off
	s_barrier
	s_waitcnt lgkmcnt(0)
	s_setprio 1
	s_waitcnt lgkmcnt(0)
	v_mfma_f32_16x16x32_bf16 v[60:63], v[134:137], v[156:159], v[60:63]
	v_mfma_f32_16x16x32_bf16 v[56:59], v[142:145], v[156:159], v[56:59]
	v_mfma_f32_16x16x32_bf16 v[44:47], v[134:137], v[164:167], v[44:47]
	v_mfma_f32_16x16x32_bf16 v[40:43], v[142:145], v[164:167], v[40:43]
	v_mfma_f32_16x16x32_bf16 v[28:31], v[134:137], v[172:175], v[28:31]
	v_mfma_f32_16x16x32_bf16 v[24:27], v[142:145], v[172:175], v[24:27]
	v_mfma_f32_16x16x32_bf16 v[12:15], v[134:137], v[204:207], v[12:15]
	v_mfma_f32_16x16x32_bf16 v[8:11], v[142:145], v[204:207], v[8:11]
	v_mfma_f32_16x16x32_bf16 v[60:63], v[138:141], v[160:163], v[60:63]
	v_mfma_f32_16x16x32_bf16 v[56:59], v[146:149], v[160:163], v[56:59]
	v_mfma_f32_16x16x32_bf16 v[44:47], v[138:141], v[168:171], v[44:47]
	v_mfma_f32_16x16x32_bf16 v[40:43], v[146:149], v[168:171], v[40:43]
	v_mfma_f32_16x16x32_bf16 v[28:31], v[138:141], v[176:179], v[28:31]
	v_mfma_f32_16x16x32_bf16 v[24:27], v[146:149], v[176:179], v[24:27]
	v_mfma_f32_16x16x32_bf16 v[12:15], v[138:141], v[208:211], v[12:15]
	v_mfma_f32_16x16x32_bf16 v[8:11], v[146:149], v[208:211], v[8:11]
	s_setprio 0
	s_barrier
	s_add_u32 s28, s34, 0x40080
	s_addc_u32 s29, s35, 0
	s_add_i32 s34, s36, s44
	v_lshl_add_u64 v[134:135], s[28:29], 0, v[180:181]
	s_mov_b32 m0, s34
	s_nop 0
	global_load_lds_dwordx4 v[134:135], off
	v_lshl_add_u64 v[134:135], s[28:29], 0, v[128:129]
	s_add_i32 m0, s34, 0x2000
	s_nop 0
	global_load_lds_dwordx4 v[134:135], off
	s_waitcnt vmcnt(6)
	s_barrier
	s_setprio 1
	v_mfma_f32_16x16x32_bf16 v[52:55], v[212:215], v[156:159], v[52:55]
	v_mfma_f32_16x16x32_bf16 v[48:51], v[220:223], v[156:159], v[48:51]
	v_mfma_f32_16x16x32_bf16 v[36:39], v[212:215], v[164:167], v[36:39]
	v_mfma_f32_16x16x32_bf16 v[32:35], v[220:223], v[164:167], v[32:35]
	v_mfma_f32_16x16x32_bf16 v[20:23], v[212:215], v[172:175], v[20:23]
	v_mfma_f32_16x16x32_bf16 v[16:19], v[220:223], v[172:175], v[16:19]
	v_mfma_f32_16x16x32_bf16 v[4:7], v[212:215], v[204:207], v[4:7]
	v_mfma_f32_16x16x32_bf16 v[0:3], v[220:223], v[204:207], v[0:3]
	v_mfma_f32_16x16x32_bf16 v[52:55], v[216:219], v[160:163], v[52:55]
	v_mfma_f32_16x16x32_bf16 v[48:51], v[224:227], v[160:163], v[48:51]
	v_mfma_f32_16x16x32_bf16 v[36:39], v[216:219], v[168:171], v[36:39]
	v_mfma_f32_16x16x32_bf16 v[32:35], v[224:227], v[168:171], v[32:35]
	v_mfma_f32_16x16x32_bf16 v[20:23], v[216:219], v[176:179], v[20:23]
	v_mfma_f32_16x16x32_bf16 v[16:19], v[224:227], v[176:179], v[16:19]
	v_mfma_f32_16x16x32_bf16 v[4:7], v[216:219], v[208:211], v[4:7]
	v_mfma_f32_16x16x32_bf16 v[0:3], v[224:227], v[208:211], v[0:3]
	s_setprio 0
	s_add_i32 s57, s57, 2
	s_add_u32 s55, s55, 0x100
	s_addc_u32 s56, s56, 0
	s_cmp_gt_u32 s57, 13
	s_mov_b64 s[28:29], s[30:31]
	s_barrier
	s_cbranch_scc0 .LBB0_234
	v_lshl_add_u32 v138, s6, 8, v152
	v_cndmask_b32_e64 v134, 0, 1, s[16:17]
	v_cmp_ne_u32_e64 s[6:7], 1, v134
	s_andn2_b64 vcc, exec, s[16:17]
	v_ashrrev_i32_e32 v139, 31, v138
	s_cbranch_vccnz .LBB0_237
	v_readlane_b32 s28, v254, 33
	v_readlane_b32 s29, v254, 34
	s_nop 1
	v_lshl_add_u64 v[134:135], v[138:139], 3, s[28:29]
	global_load_dwordx2 v[144:145], v[134:135], off
	global_load_dwordx2 v[226:227], v[134:135], off offset:128
	global_load_dwordx2 v[232:233], v[134:135], off offset:256
	global_load_dwordx2 v[234:235], v[134:135], off offset:384
	global_load_dwordx2 v[242:243], v[134:135], off offset:1024
	global_load_dwordx2 v[244:245], v[134:135], off offset:1152
	global_load_dwordx2 v[250:251], v[134:135], off offset:1280
	s_waitcnt vmcnt(0)
	v_mov_b32_e32 v146, v145
	s_branch .LBB0_238

; __device__ __forceinline__ void row_stats(const float* mur, int row, float& mu, float& rstd) {
;     if (mur) { const float2 v = *(const float2*)(mur + 2 * (size_t)row); mu = v.x; rstd = v.y; }
;     else { mu = 0.f; rstd = 1.f; }
;     __device__ __forceinline__ void operator()(const f32x4 (&acc)[2][2][4][2], const pg8::Unit& u, int wr, int wc, int fr, int fq) const {
;     ...
;                 const int row = row0 + ai * 128 + m * 16; float mu, rstd; row_stats(stats_prev, row, mu, rstd);
.LBB0_248:
	s_or_b64 exec, exec, s[28:29]
	v_or_b32_e32 v112, 16, v138
	s_and_b64 vcc, exec, s[6:7]
	v_ashrrev_i32_e32 v113, 31, v112
	s_cbranch_vccnz .LBB0_250
	v_readlane_b32 s28, v254, 33
	v_readlane_b32 s29, v254, 34
	s_waitcnt lgkmcnt(0)
	s_nop 0
	v_mov_b32_e32 v116, v226
	v_mov_b32_e32 v117, v227
	v_mov_b32_e32 v118, v117
	s_branch .LBB0_251

; __device__ __forceinline__ void row_stats(const float* mur, int row, float& mu, float& rstd) {
;     if (mur) { const float2 v = *(const float2*)(mur + 2 * (size_t)row); mu = v.x; rstd = v.y; }
;     else { mu = 0.f; rstd = 1.f; }
;     __device__ __forceinline__ void operator()(const f32x4 (&acc)[2][2][4][2], const pg8::Unit& u, int wr, int wc, int fr, int fq) const {
;     ...
;                 const int row = row0 + ai * 128 + m * 16; float mu, rstd; row_stats(stats_prev, row, mu, rstd);
.LBB0_261:
	s_or_b64 exec, exec, s[28:29]
	v_or_b32_e32 v96, 32, v138
	s_and_b64 vcc, exec, s[6:7]
	v_ashrrev_i32_e32 v97, 31, v96
	s_cbranch_vccnz .LBB0_263
	v_readlane_b32 s28, v254, 33
	v_readlane_b32 s29, v254, 34
	s_waitcnt lgkmcnt(0)
	s_nop 0
	v_mov_b32_e32 v100, v232
	v_mov_b32_e32 v101, v233
	v_mov_b32_e32 v102, v101
	s_branch .LBB0_264

; __device__ __forceinline__ void row_stats(const float* mur, int row, float& mu, float& rstd) {
;     if (mur) { const float2 v = *(const float2*)(mur + 2 * (size_t)row); mu = v.x; rstd = v.y; }
;     else { mu = 0.f; rstd = 1.f; }
;     __device__ __forceinline__ void operator()(const f32x4 (&acc)[2][2][4][2], const pg8::Unit& u, int wr, int wc, int fr, int fq) const {
;     ...
;                 const int row = row0 + ai * 128 + m * 16; float mu, rstd; row_stats(stats_prev, row, mu, rstd);
.LBB0_274:
	s_or_b64 exec, exec, s[28:29]
	v_or_b32_e32 v80, 48, v138
	s_and_b64 vcc, exec, s[6:7]
	v_ashrrev_i32_e32 v81, 31, v80
	s_cbranch_vccnz .LBB0_276
	v_readlane_b32 s28, v254, 33
	v_readlane_b32 s29, v254, 34
	s_waitcnt lgkmcnt(0)
	s_nop 0
	v_mov_b32_e32 v84, v234
	v_mov_b32_e32 v85, v235
	v_mov_b32_e32 v86, v85
	s_branch .LBB0_277

; __device__ __forceinline__ void row_stats(const float* mur, int row, float& mu, float& rstd) {
;     if (mur) { const float2 v = *(const float2*)(mur + 2 * (size_t)row); mu = v.x; rstd = v.y; }
;     else { mu = 0.f; rstd = 1.f; }
;     __device__ __forceinline__ void operator()(const f32x4 (&acc)[2][2][4][2], const pg8::Unit& u, int wr, int wc, int fr, int fq) const {
;     ...
;                 const int row = row0 + ai * 128 + m * 16; float mu, rstd; row_stats(stats_prev, row, mu, rstd);
.LBB0_287:
	s_or_b64 exec, exec, s[28:29]
	v_add_u32_e32 v64, 0x80, v138
	s_and_b64 vcc, exec, s[6:7]
	v_ashrrev_i32_e32 v65, 31, v64
	s_cbranch_vccnz .LBB0_289
	v_readlane_b32 s28, v254, 33
	v_readlane_b32 s29, v254, 34
	s_waitcnt lgkmcnt(0)
	s_nop 0
	v_mov_b32_e32 v68, v242
	v_mov_b32_e32 v69, v243
	v_mov_b32_e32 v70, v69
	s_branch .LBB0_290

; __device__ __forceinline__ void row_stats(const float* mur, int row, float& mu, float& rstd) {
;     if (mur) { const float2 v = *(const float2*)(mur + 2 * (size_t)row); mu = v.x; rstd = v.y; }
;     else { mu = 0.f; rstd = 1.f; }
;     __device__ __forceinline__ void operator()(const f32x4 (&acc)[2][2][4][2], const pg8::Unit& u, int wr, int wc, int fr, int fq) const {
;     ...
;                 const int row = row0 + ai * 128 + m * 16; float mu, rstd; row_stats(stats_prev, row, mu, rstd);
.LBB0_300:
	s_or_b64 exec, exec, s[28:29]
	v_add_u32_e32 v48, 0x90, v138
	s_and_b64 vcc, exec, s[6:7]
	v_ashrrev_i32_e32 v49, 31, v48
	s_cbranch_vccnz .LBB0_302
	v_readlane_b32 s28, v254, 33
	v_readlane_b32 s29, v254, 34
	s_waitcnt lgkmcnt(0)
	s_nop 0
	v_mov_b32_e32 v52, v244
	v_mov_b32_e32 v53, v245
	v_mov_b32_e32 v54, v53
	s_branch .LBB0_303

; __device__ __forceinline__ void row_stats(const float* mur, int row, float& mu, float& rstd) {
;     if (mur) { const float2 v = *(const float2*)(mur + 2 * (size_t)row); mu = v.x; rstd = v.y; }
;     else { mu = 0.f; rstd = 1.f; }
;     __device__ __forceinline__ void operator()(const f32x4 (&acc)[2][2][4][2], const pg8::Unit& u, int wr, int wc, int fr, int fq) const {
;     ...
;                 const int row = row0 + ai * 128 + m * 16; float mu, rstd; row_stats(stats_prev, row, mu, rstd);
.LBB0_313:
	s_or_b64 exec, exec, s[28:29]
	v_add_u32_e32 v32, 0xa0, v138
	s_and_b64 vcc, exec, s[6:7]
	v_ashrrev_i32_e32 v33, 31, v32
	s_cbranch_vccnz .LBB0_315
	v_readlane_b32 s28, v254, 33
	v_readlane_b32 s29, v254, 34
	s_waitcnt lgkmcnt(0)
	s_nop 0
	v_mov_b32_e32 v36, v250
	v_mov_b32_e32 v37, v251
	v_mov_b32_e32 v38, v37
	s_branch .LBB0_316

; __device__ __forceinline__ void pro_part(ArgsRef a, const Tb tb, int l, int part, int vb, int VG, LAS unsigned char* lds) {
;     ...
;             const int wv = tb.tid >> 6, lane = tb.tid & 63;
;             float* wg8 = (float*)(ws + OFF_WG8);
;             const float* W = a.in[7] + (size_t)l * D_ * NIN_;
;             float s1 = 0.f, s2 = 0.f;
;             for (int k = lane; k < D_; k += 64) { const float w = W[(size_t)k * NIN_ + NING_ + wv]; const float wgv = w * g_mix[k]; wg8[wv * 1024 + k] = wgv; s1 += wgv; s2 += b_mix[k] * w; }
.LBB0_1013:
	v_mov_b64_e32 v[16:17], v[10:11]
	global_load_dword v20, v[16:17], off
	global_load_dword v36, v[8:9], off
	global_load_dword v52, v[6:7], off
	v_lshl_add_u64 v[16:17], v[16:17], 0, s[10:11]
	global_load_dword v21, v[16:17], off
	global_load_dword v37, v[8:9], off offset:256
	global_load_dword v53, v[6:7], off offset:256
	v_lshl_add_u64 v[16:17], v[16:17], 0, s[10:11]
	global_load_dword v22, v[16:17], off
	global_load_dword v38, v[8:9], off offset:512
	global_load_dword v54, v[6:7], off offset:512
	v_lshl_add_u64 v[16:17], v[16:17], 0, s[10:11]
	global_load_dword v23, v[16:17], off
	global_load_dword v39, v[8:9], off offset:768
	global_load_dword v55, v[6:7], off offset:768
	v_lshl_add_u64 v[16:17], v[16:17], 0, s[10:11]
	global_load_dword v24, v[16:17], off
	global_load_dword v40, v[8:9], off offset:1024
	global_load_dword v56, v[6:7], off offset:1024
	v_lshl_add_u64 v[16:17], v[16:17], 0, s[10:11]
	global_load_dword v25, v[16:17], off
	global_load_dword v41, v[8:9], off offset:1280
	global_load_dword v57, v[6:7], off offset:1280
	v_lshl_add_u64 v[16:17], v[16:17], 0, s[10:11]
	global_load_dword v26, v[16:17], off
	global_load_dword v42, v[8:9], off offset:1536
	global_load_dword v58, v[6:7], off offset:1536
	v_lshl_add_u64 v[16:17], v[16:17], 0, s[10:11]
	global_load_dword v27, v[16:17], off
	global_load_dword v43, v[8:9], off offset:1792
	global_load_dword v59, v[6:7], off offset:1792
	v_lshl_add_u64 v[16:17], v[16:17], 0, s[10:11]
	global_load_dword v28, v[16:17], off
	global_load_dword v44, v[8:9], off offset:2048
	global_load_dword v60, v[6:7], off offset:2048
	v_lshl_add_u64 v[16:17], v[16:17], 0, s[10:11]
	global_load_dword v29, v[16:17], off
	global_load_dword v45, v[8:9], off offset:2304
	global_load_dword v61, v[6:7], off offset:2304
	v_lshl_add_u64 v[16:17], v[16:17], 0, s[10:11]
	global_load_dword v30, v[16:17], off
	global_load_dword v46, v[8:9], off offset:2560
	global_load_dword v62, v[6:7], off offset:2560
	v_lshl_add_u64 v[16:17], v[16:17], 0, s[10:11]
	global_load_dword v31, v[16:17], off
	global_load_dword v47, v[8:9], off offset:2816
	global_load_dword v63, v[6:7], off offset:2816
	v_lshl_add_u64 v[16:17], v[16:17], 0, s[10:11]
	global_load_dword v32, v[16:17], off
	global_load_dword v48, v[8:9], off offset:3072
	global_load_dword v64, v[6:7], off offset:3072
	v_lshl_add_u64 v[16:17], v[16:17], 0, s[10:11]
	global_load_dword v33, v[16:17], off
	global_load_dword v49, v[8:9], off offset:3328
	global_load_dword v65, v[6:7], off offset:3328
	v_lshl_add_u64 v[16:17], v[16:17], 0, s[10:11]
	global_load_dword v34, v[16:17], off
	global_load_dword v50, v[8:9], off offset:3584
	global_load_dword v66, v[6:7], off offset:3584
	v_lshl_add_u64 v[16:17], v[16:17], 0, s[10:11]
	global_load_dword v35, v[16:17], off
	global_load_dword v51, v[8:9], off offset:3840
	global_load_dword v67, v[6:7], off offset:3840
	s_waitcnt vmcnt(0)
; __device__ __forceinline__ void pro_part(ArgsRef a, const Tb tb, int l, int part, int vb, int VG, LAS unsigned char* lds) {
;     ...
;             for (int k = lane; k < D_; k += 64) { const float w = W[(size_t)k * NIN_ + NING_ + wv]; const float wgv = w * g_mix[k]; wg8[wv * 1024 + k] = wgv; s1 += wgv; s2 += b_mix[k] * w; }
;             s1 = wave_sum(s1); s2 = wave_sum(s2);
;             if (lane == 0) { wg8[8192 + wv] = s1; wg8[8192 + 8 + wv] = s2; }
	v_mul_f32_e32 v36, v20, v36
	global_store_dword v[4:5], v36, off
	v_mul_f32_e32 v52, v20, v52
	v_add_f32_e32 v2, v2, v36
	v_add_f32_e32 v3, v3, v52
	v_mul_f32_e32 v37, v21, v37
	global_store_dword v[4:5], v37, off offset:256
	v_mul_f32_e32 v53, v21, v53
	v_add_f32_e32 v2, v2, v37
	v_add_f32_e32 v3, v3, v53
	v_mul_f32_e32 v38, v22, v38
	global_store_dword v[4:5], v38, off offset:512
	v_mul_f32_e32 v54, v22, v54
	v_add_f32_e32 v2, v2, v38
	v_add_f32_e32 v3, v3, v54
	v_mul_f32_e32 v39, v23, v39
	global_store_dword v[4:5], v39, off offset:768
	v_mul_f32_e32 v55, v23, v55
	v_add_f32_e32 v2, v2, v39
	v_add_f32_e32 v3, v3, v55
	v_mul_f32_e32 v40, v24, v40
	global_store_dword v[4:5], v40, off offset:1024
	v_mul_f32_e32 v56, v24, v56
	v_add_f32_e32 v2, v2, v40
	v_add_f32_e32 v3, v3, v56
	v_mul_f32_e32 v41, v25, v41
	global_store_dword v[4:5], v41, off offset:1280
	v_mul_f32_e32 v57, v25, v57
	v_add_f32_e32 v2, v2, v41
	v_add_f32_e32 v3, v3, v57
	v_mul_f32_e32 v42, v26, v42
	global_store_dword v[4:5], v42, off offset:1536
	v_mul_f32_e32 v58, v26, v58
	v_add_f32_e32 v2, v2, v42
	v_add_f32_e32 v3, v3, v58
	v_mul_f32_e32 v43, v27, v43
	global_store_dword v[4:5], v43, off offset:1792
	v_mul_f32_e32 v59, v27, v59
	v_add_f32_e32 v2, v2, v43
	v_add_f32_e32 v3, v3, v59
	v_mul_f32_e32 v44, v28, v44
	global_store_dword v[4:5], v44, off offset:2048
	v_mul_f32_e32 v60, v28, v60
	v_add_f32_e32 v2, v2, v44
	v_add_f32_e32 v3, v3, v60
	v_mul_f32_e32 v45, v29, v45
	global_store_dword v[4:5], v45, off offset:2304
	v_mul_f32_e32 v61, v29, v61
	v_add_f32_e32 v2, v2, v45
	v_add_f32_e32 v3, v3, v61
	v_mul_f32_e32 v46, v30, v46
	global_store_dword v[4:5], v46, off offset:2560
	v_mul_f32_e32 v62, v30, v62
	v_add_f32_e32 v2, v2, v46
	v_add_f32_e32 v3, v3, v62
	v_mul_f32_e32 v47, v31, v47
	global_store_dword v[4:5], v47, off offset:2816
	v_mul_f32_e32 v63, v31, v63
	v_add_f32_e32 v2, v2, v47
	v_add_f32_e32 v3, v3, v63
	v_mul_f32_e32 v48, v32, v48
	global_store_dword v[4:5], v48, off offset:3072
	v_mul_f32_e32 v64, v32, v64
	v_add_f32_e32 v2, v2, v48
	v_add_f32_e32 v3, v3, v64
	v_mul_f32_e32 v49, v33, v49
	global_store_dword v[4:5], v49, off offset:3328
	v_mul_f32_e32 v65, v33, v65
	v_add_f32_e32 v2, v2, v49
	v_add_f32_e32 v3, v3, v65
	v_mul_f32_e32 v50, v34, v50
	global_store_dword v[4:5], v50, off offset:3584
	v_mul_f32_e32 v66, v34, v66
	v_add_f32_e32 v2, v2, v50
	v_add_f32_e32 v3, v3, v66
	v_mul_f32_e32 v51, v35, v51
	global_store_dword v[4:5], v51, off offset:3840
	v_mul_f32_e32 v67, v35, v67
	v_add_f32_e32 v2, v2, v51
	v_add_f32_e32 v3, v3, v67
	s_or_b64 exec, exec, s[4:5]
	v_cmp_lt_i32_e32 vcc, v237, v239
	s_nop 1
	v_cndmask_b32_e32 v4, v236, v237, vcc
	v_lshlrev_b32_e32 v5, 2, v4
	ds_bpermute_b32 v4, v5, v2
	v_cmp_lt_i32_e32 vcc, v240, v239
	ds_bpermute_b32 v5, v5, v3
	s_waitcnt lgkmcnt(1)
	v_add_f32_e32 v2, v2, v4
	v_cndmask_b32_e32 v4, v236, v240, vcc
	v_lshlrev_b32_e32 v6, 2, v4
	ds_bpermute_b32 v4, v6, v2
	v_cmp_lt_i32_e32 vcc, v241, v239
	s_waitcnt lgkmcnt(1)
	v_add_f32_e32 v3, v3, v5
	ds_bpermute_b32 v5, v6, v3
	s_waitcnt lgkmcnt(1)
	v_add_f32_e32 v2, v2, v4
	v_cndmask_b32_e32 v4, v236, v241, vcc
	v_lshlrev_b32_e32 v7, 2, v4
	ds_bpermute_b32 v4, v7, v2
	s_waitcnt lgkmcnt(1)
	v_add_f32_e32 v3, v3, v5
	ds_bpermute_b32 v5, v7, v3
	s_waitcnt lgkmcnt(1)
	v_add_f32_e32 v2, v2, v4
	v_xor_b32_e32 v4, 8, v236
	v_cmp_lt_i32_e32 vcc, v4, v239
	s_waitcnt lgkmcnt(0)
	v_add_f32_e32 v3, v3, v5
	v_cndmask_b32_e32 v4, v236, v4, vcc
	v_lshlrev_b32_e32 v8, 2, v4
	ds_bpermute_b32 v4, v8, v2
	ds_bpermute_b32 v5, v8, v3
	s_waitcnt lgkmcnt(1)
	v_add_f32_e32 v2, v2, v4
	v_xor_b32_e32 v4, 16, v236
	v_cmp_lt_i32_e32 vcc, v4, v239
	s_waitcnt lgkmcnt(0)
	v_add_f32_e32 v3, v3, v5
	v_cndmask_b32_e32 v4, v236, v4, vcc
	v_lshlrev_b32_e32 v9, 2, v4
	ds_bpermute_b32 v4, v9, v2
	ds_bpermute_b32 v5, v9, v3
	s_waitcnt lgkmcnt(1)
	v_add_f32_e32 v2, v2, v4
	v_xor_b32_e32 v4, 32, v236
	v_cmp_lt_i32_e32 vcc, v4, v239
	s_waitcnt lgkmcnt(0)
	v_add_f32_e32 v3, v3, v5
	v_cndmask_b32_e32 v4, v236, v4, vcc
	v_lshlrev_b32_e32 v10, 2, v4
	ds_bpermute_b32 v4, v10, v2
	ds_bpermute_b32 v5, v10, v3
	v_cmp_eq_u32_e32 vcc, 0, v12
	s_and_saveexec_b64 s[4:5], vcc
	s_cbranch_execz .LBB0_1016
	v_lshl_add_u64 v[0:1], v[0:1], 2, s[2:3]
	v_add_co_u32_e32 v0, vcc, 0x8000, v0
	s_waitcnt lgkmcnt(1)
	v_add_f32_e32 v2, v2, v4
	v_addc_co_u32_e32 v1, vcc, 0, v1, vcc
	s_waitcnt lgkmcnt(0)
	v_add_f32_e32 v3, v3, v5
	global_store_dword v[0:1], v2, off
	global_store_dword v[0:1], v3, off offset:32

; __device__ __forceinline__ void row_stats(const float* mur, int row, float& mu, float& rstd) {
;     if (mur) { const float2 v = *(const float2*)(mur + 2 * (size_t)row); mu = v.x; rstd = v.y; }
;     else { mu = 0.f; rstd = 1.f; }
;     __device__ __forceinline__ void operator()(const f32x4 (&acc)[2][2][4][2], const pg8::Unit& u, int wr, int wc, int fr, int fq) const {
;     ...
;                 const int row = row0 + ai * 128 + m * 16; float mu, rstd; row_stats(stats, row, mu, rstd);
.LBB0_1290:
	v_cndmask_b32_e64 v128, 0, 1, s[8:9]
	v_add_u32_e32 v152, s4, v170
	v_cmp_ne_u32_e64 s[4:5], 1, v128
	s_andn2_b64 vcc, exec, s[8:9]
	s_cbranch_vccnz .LBB0_1292
	v_ashrrev_i32_e32 v153, 31, v152
	v_lshl_add_u64 v[128:129], v[152:153], 3, s[54:55]
	global_load_dwordx2 v[156:157], v[128:129], off
	global_load_dword v242, v[128:129], off offset:128
	global_load_dword v243, v[128:129], off offset:132
	global_load_dword v244, v[128:129], off offset:256
	global_load_dword v245, v[128:129], off offset:260
	global_load_dword v200, v[128:129], off offset:384
	global_load_dword v202, v[128:129], off offset:388
	s_waitcnt vmcnt(0)
	v_mov_b32_e32 v154, v157
	s_branch .LBB0_1293

; __device__ __forceinline__ void row_stats(const float* mur, int row, float& mu, float& rstd) {
;     if (mur) { const float2 v = *(const float2*)(mur + 2 * (size_t)row); mu = v.x; rstd = v.y; }
;     else { mu = 0.f; rstd = 1.f; }
;     __device__ __forceinline__ void operator()(const f32x4 (&acc)[2][2][4][2], const pg8::Unit& u, int wr, int wc, int fr, int fq) const {
;     ...
;                 const int row = row0 + ai * 128 + m * 16; float mu, rstd; row_stats(stats, row, mu, rstd);
.LBB0_1324:
	v_ashrrev_i32_e32 v161, 31, v160
	v_mov_b32_e32 v156, v242
	v_mov_b32_e32 v157, v243
	v_mov_b32_e32 v154, v157
	v_mov_b64_e32 v[132:133], v[204:205]
	v_mov_b64_e32 v[134:135], v[206:207]
	v_mov_b64_e32 v[128:129], v[208:209]
	v_mov_b64_e32 v[130:131], v[210:211]
	s_cmp_lt_i32 s6, 5
	s_cbranch_scc1 .LBB0_1329

; __device__ __forceinline__ void row_stats(const float* mur, int row, float& mu, float& rstd) {
;     if (mur) { const float2 v = *(const float2*)(mur + 2 * (size_t)row); mu = v.x; rstd = v.y; }
;     else { mu = 0.f; rstd = 1.f; }
;     __device__ __forceinline__ void operator()(const f32x4 (&acc)[2][2][4][2], const pg8::Unit& u, int wr, int wc, int fr, int fq) const {
;     ...
;                 const int row = row0 + ai * 128 + m * 16; float mu, rstd; row_stats(stats, row, mu, rstd);
.LBB0_1358:
	v_ashrrev_i32_e32 v161, 31, v160
	v_mov_b32_e32 v156, v244
	v_mov_b32_e32 v157, v245
	v_mov_b32_e32 v154, v157
	v_mov_b64_e32 v[132:133], v[204:205]
	v_mov_b64_e32 v[134:135], v[206:207]
	v_mov_b64_e32 v[128:129], v[208:209]
	v_mov_b64_e32 v[130:131], v[210:211]
	s_cmp_lt_i32 s6, 5
	s_cbranch_scc1 .LBB0_1363

; __device__ __forceinline__ void row_stats(const float* mur, int row, float& mu, float& rstd) {
;     if (mur) { const float2 v = *(const float2*)(mur + 2 * (size_t)row); mu = v.x; rstd = v.y; }
;     else { mu = 0.f; rstd = 1.f; }
;     __device__ __forceinline__ void operator()(const f32x4 (&acc)[2][2][4][2], const pg8::Unit& u, int wr, int wc, int fr, int fq) const {
;     ...
;                 const int row = row0 + ai * 128 + m * 16; float mu, rstd; row_stats(stats, row, mu, rstd);
.LBB0_1392:
	v_ashrrev_i32_e32 v159, 31, v158
	v_mov_b32_e32 v154, v200
	v_mov_b32_e32 v155, v202
	v_mov_b32_e32 v152, v155
	v_mov_b64_e32 v[132:133], v[204:205]
	v_mov_b64_e32 v[134:135], v[206:207]
	v_mov_b64_e32 v[128:129], v[208:209]
	v_mov_b64_e32 v[130:131], v[210:211]
	s_cmp_lt_i32 s6, 5
	s_cbranch_scc1 .LBB0_1397

; #define PG8_STAGE(bufoff, gbase, voff) do { _Pragma("unroll") for (int _i = 0; _i < 2; ++_i) \
;         __builtin_amdgcn_global_load_lds((const unsigned*)((const char*)(gbase) + (voff)[_i]), (LAS unsigned*)(lds + (bufoff) + ldsw + _i * 8192), 16, 0, 0); } while (0)
; #define PG8_LDA(dst, b, h) do { _Pragma("unroll") for (int m = 0; m < 4; ++m) _Pragma("unroll") for (int k = 0; k < 2; ++k) dst[m][k] = *(const LAS bf16x8*)(lds + PG8_SA(b, h) + aoff + m * 2048 + k * 1024); } while (0)
; #define PG8_LDB(dst, b, h) do { _Pragma("unroll") for (int n = 0; n < 2; ++n) _Pragma("unroll") for (int k = 0; k < 2; ++k) dst[n][k] = *(const LAS bf16x8*)(lds + PG8_SB(b, h) + boff + n * 2048 + k * 1024); } while (0)
; #define PG8_MMA(ai, bj, At, Bt) do { __builtin_amdgcn_s_setprio(1); _Pragma("unroll") for (int m = 0; m < 4; ++m) _Pragma("unroll") for (int n = 0; n < 2; ++n) _Pragma("unroll") for (int k = 0; k < 2; ++k) \
;         acc[ai][bj][m][n] = __builtin_amdgcn_mfma_f32_16x16x32_bf16(Bt[n][k], At[m][k], acc[ai][bj][m][n], 0, 0, 0); __builtin_amdgcn_s_setprio(0); } while (0)
; #define PG8_WAIT_V(n) asm volatile("s_waitcnt vmcnt(" #n ")" ::: "memory")
; #define PG8_WAIT_L(n) asm volatile("s_waitcnt lgkmcnt(" #n ")" ::: "memory")
; template <class Epi>
; __device__ __forceinline__ void gemm_phase(const Tb tb, LAS unsigned char* lds, const Gemm g, const StaticOrder& S, const Epi& E) {
;     ...
;         for (int t = 0; t < nt; t += 2) {
;             const bool last = (t == nt - 2);
;             const char* a1 = cA + (size_t)(t + 1) * kstep;
;             const char* a2 = last ? nA : cA + (size_t)(t + 2) * kstep; const char* b2 = last ? nB : cB + (size_t)(t + 2) * kstep;
;             const char* a3 = a2 + kstep; const char* b3 = b2 + kstep;
;             PG8_LDB(B0, 0, 0); PG8_SCHED; PG8_LDA(At, 0, 0); PG8_STAGE(PG8_SA(1, 1), a1 + hstep, voffA);
;             PG8_WAIT_L(8); PG8_BAR; PG8_WAIT_L(0); PG8_MMA(0, 0, At, B0); PG8_BAR; PG8_SCHED;
;             PG8_LDB(B1, 0, 1); PG8_STAGE(PG8_SB(0, 0), b2, voffB);
;             PG8_BAR; PG8_WAIT_L(0); PG8_MMA(0, 1, At, B1); PG8_BAR;
;             PG8_LDA(At, 0, 1); PG8_STAGE(PG8_SA(0, 0), a2, voffA);
;             PG8_BAR; PG8_WAIT_L(0); PG8_MMA(1, 0, At, B0); PG8_BAR; PG8_SCHED;
;             PG8_STAGE(PG8_SB(0, 1), b2 + hstep, voffB);
;             PG8_WAIT_V(6); PG8_BAR; PG8_MMA(1, 1, At, B1); PG8_BAR;
.LBB0_1465:
	s_add_u32 s6, s22, 0x100
	s_addc_u32 s7, s23, 0
	s_add_i32 s52, 0, 0x10000
	v_add_u32_e32 v146, s52, v153
	ds_read_b128 v[134:137], v146
	ds_read_b128 v[138:141], v146 offset:1024
	ds_read_b128 v[142:145], v146 offset:2048
	ds_read_b128 v[146:149], v146 offset:3072
	s_cmp_eq_u32 s51, 40
	s_cselect_b32 s27, s21, s7
	s_cselect_b32 s26, s20, s6
	s_cselect_b32 s25, s9, s50
	s_cselect_b32 s24, s8, s49
	v_lshl_add_u64 v[150:151], s[22:23], 0, v[132:133]
	s_add_i32 m0, s36, 0xc000
	ds_read_b128 v[156:159], v155
	ds_read_b128 v[160:163], v155 offset:1024
	ds_read_b128 v[164:167], v155 offset:2048
	ds_read_b128 v[168:171], v155 offset:3072
	ds_read_b128 v[172:175], v155 offset:4096
	ds_read_b128 v[176:179], v155 offset:5120
	ds_read_b128 v[204:207], v155 offset:6144
	ds_read_b128 v[208:211], v155 offset:7168
	global_load_lds_dwordx4 v[150:151], off
	v_lshl_add_u64 v[150:151], s[22:23], 0, v[130:131]
	s_add_i32 m0, s36, 0xe000
	s_nop 0
	global_load_lds_dwordx4 v[150:151], off
	s_waitcnt lgkmcnt(8)
	s_barrier
	s_waitcnt lgkmcnt(0)
	s_setprio 1
	s_waitcnt lgkmcnt(0)
	v_mfma_f32_16x16x32_bf16 v[124:127], v[134:137], v[156:159], v[124:127]
	v_mfma_f32_16x16x32_bf16 v[120:123], v[142:145], v[156:159], v[120:123]
	v_mfma_f32_16x16x32_bf16 v[108:111], v[134:137], v[164:167], v[108:111]
	v_mfma_f32_16x16x32_bf16 v[104:107], v[142:145], v[164:167], v[104:107]
	v_mfma_f32_16x16x32_bf16 v[92:95], v[134:137], v[172:175], v[92:95]
	v_mfma_f32_16x16x32_bf16 v[88:91], v[142:145], v[172:175], v[88:91]
	v_mfma_f32_16x16x32_bf16 v[76:79], v[134:137], v[204:207], v[76:79]
	v_mfma_f32_16x16x32_bf16 v[72:75], v[142:145], v[204:207], v[72:75]
	v_mfma_f32_16x16x32_bf16 v[124:127], v[138:141], v[160:163], v[124:127]
	v_mfma_f32_16x16x32_bf16 v[120:123], v[146:149], v[160:163], v[120:123]
	v_mfma_f32_16x16x32_bf16 v[108:111], v[138:141], v[168:171], v[108:111]
	v_mfma_f32_16x16x32_bf16 v[104:107], v[146:149], v[168:171], v[104:107]
	v_mfma_f32_16x16x32_bf16 v[92:95], v[138:141], v[176:179], v[92:95]
	v_mfma_f32_16x16x32_bf16 v[88:91], v[146:149], v[176:179], v[88:91]
	v_mfma_f32_16x16x32_bf16 v[76:79], v[138:141], v[208:211], v[76:79]
	v_mfma_f32_16x16x32_bf16 v[72:75], v[146:149], v[208:211], v[72:75]
	s_setprio 0
	s_barrier
	s_add_i32 s53, 0, 0x14000
	v_add_u32_e32 v150, s53, v153
	s_add_i32 s22, s52, s35
	ds_read_b128 v[212:215], v150
	ds_read_b128 v[216:219], v150 offset:1024
	ds_read_b128 v[220:223], v150 offset:2048
	ds_read_b128 v[224:227], v150 offset:3072
	v_lshl_add_u64 v[150:151], s[24:25], 0, v[180:181]
	s_mov_b32 m0, s22
	v_lshl_add_u64 v[198:199], s[24:25], 0, v[128:129]
	global_load_lds_dwordx4 v[150:151], off
	s_add_i32 m0, s22, 0x2000
	s_nop 0
	global_load_lds_dwordx4 v[198:199], off
	s_barrier
	s_waitcnt lgkmcnt(0)
	s_setprio 1
	s_waitcnt lgkmcnt(0)
	v_mfma_f32_16x16x32_bf16 v[116:119], v[212:215], v[156:159], v[116:119]
	v_mfma_f32_16x16x32_bf16 v[112:115], v[220:223], v[156:159], v[112:115]
	v_mfma_f32_16x16x32_bf16 v[100:103], v[212:215], v[164:167], v[100:103]
	v_mfma_f32_16x16x32_bf16 v[96:99], v[220:223], v[164:167], v[96:99]
	v_mfma_f32_16x16x32_bf16 v[84:87], v[212:215], v[172:175], v[84:87]
	v_mfma_f32_16x16x32_bf16 v[80:83], v[220:223], v[172:175], v[80:83]
	v_mfma_f32_16x16x32_bf16 v[68:71], v[212:215], v[204:207], v[68:71]
	v_mfma_f32_16x16x32_bf16 v[64:67], v[220:223], v[204:207], v[64:67]
	v_mfma_f32_16x16x32_bf16 v[116:119], v[216:219], v[160:163], v[116:119]
	v_mfma_f32_16x16x32_bf16 v[112:115], v[224:227], v[160:163], v[112:115]
	v_mfma_f32_16x16x32_bf16 v[100:103], v[216:219], v[168:171], v[100:103]
	v_mfma_f32_16x16x32_bf16 v[96:99], v[224:227], v[168:171], v[96:99]
	v_mfma_f32_16x16x32_bf16 v[84:87], v[216:219], v[176:179], v[84:87]
	v_mfma_f32_16x16x32_bf16 v[80:83], v[224:227], v[176:179], v[80:83]
	v_mfma_f32_16x16x32_bf16 v[68:71], v[216:219], v[208:211], v[68:71]
	v_mfma_f32_16x16x32_bf16 v[64:67], v[224:227], v[208:211], v[64:67]
	s_setprio 0
	s_mov_b32 m0, s36
	v_lshl_add_u64 v[228:229], s[26:27], 0, v[180:181]
	s_barrier
	ds_read_b128 v[156:159], v155 offset:16384
	ds_read_b128 v[160:163], v155 offset:17408
	ds_read_b128 v[164:167], v155 offset:18432
	ds_read_b128 v[168:171], v155 offset:19456
	ds_read_b128 v[172:175], v155 offset:20480
	ds_read_b128 v[176:179], v155 offset:21504
	ds_read_b128 v[204:207], v155 offset:22528
	ds_read_b128 v[208:211], v155 offset:23552
	global_load_lds_dwordx4 v[228:229], off
	v_lshl_add_u64 v[230:231], s[26:27], 0, v[128:129]
	s_mov_b32 m0, s37
	s_nop 0
	global_load_lds_dwordx4 v[230:231], off
	s_barrier
	s_waitcnt lgkmcnt(0)
	s_setprio 1
	s_waitcnt lgkmcnt(0)
	v_mfma_f32_16x16x32_bf16 v[60:63], v[134:137], v[156:159], v[60:63]
	v_mfma_f32_16x16x32_bf16 v[56:59], v[142:145], v[156:159], v[56:59]
	v_mfma_f32_16x16x32_bf16 v[44:47], v[134:137], v[164:167], v[44:47]
	v_mfma_f32_16x16x32_bf16 v[40:43], v[142:145], v[164:167], v[40:43]
	v_mfma_f32_16x16x32_bf16 v[28:31], v[134:137], v[172:175], v[28:31]
	v_mfma_f32_16x16x32_bf16 v[24:27], v[142:145], v[172:175], v[24:27]
	v_mfma_f32_16x16x32_bf16 v[12:15], v[134:137], v[204:207], v[12:15]
	v_mfma_f32_16x16x32_bf16 v[8:11], v[142:145], v[204:207], v[8:11]
	v_mfma_f32_16x16x32_bf16 v[60:63], v[138:141], v[160:163], v[60:63]
	v_mfma_f32_16x16x32_bf16 v[56:59], v[146:149], v[160:163], v[56:59]
	v_mfma_f32_16x16x32_bf16 v[44:47], v[138:141], v[168:171], v[44:47]
	v_mfma_f32_16x16x32_bf16 v[40:43], v[146:149], v[168:171], v[40:43]
	v_mfma_f32_16x16x32_bf16 v[28:31], v[138:141], v[176:179], v[28:31]
	v_mfma_f32_16x16x32_bf16 v[24:27], v[146:149], v[176:179], v[24:27]
	v_mfma_f32_16x16x32_bf16 v[12:15], v[138:141], v[208:211], v[12:15]
	v_mfma_f32_16x16x32_bf16 v[8:11], v[146:149], v[208:211], v[8:11]
	s_setprio 0
	s_barrier
; #define PG8_STAGE(bufoff, gbase, voff) do { _Pragma("unroll") for (int _i = 0; _i < 2; ++_i) \
;         __builtin_amdgcn_global_load_lds((const unsigned*)((const char*)(gbase) + (voff)[_i]), (LAS unsigned*)(lds + (bufoff) + ldsw + _i * 8192), 16, 0, 0); } while (0)
; #define PG8_LDA(dst, b, h) do { _Pragma("unroll") for (int m = 0; m < 4; ++m) _Pragma("unroll") for (int k = 0; k < 2; ++k) dst[m][k] = *(const LAS bf16x8*)(lds + PG8_SA(b, h) + aoff + m * 2048 + k * 1024); } while (0)
; #define PG8_LDB(dst, b, h) do { _Pragma("unroll") for (int n = 0; n < 2; ++n) _Pragma("unroll") for (int k = 0; k < 2; ++k) dst[n][k] = *(const LAS bf16x8*)(lds + PG8_SB(b, h) + boff + n * 2048 + k * 1024); } while (0)
; #define PG8_MMA(ai, bj, At, Bt) do { __builtin_amdgcn_s_setprio(1); _Pragma("unroll") for (int m = 0; m < 4; ++m) _Pragma("unroll") for (int n = 0; n < 2; ++n) _Pragma("unroll") for (int k = 0; k < 2; ++k) \
;         acc[ai][bj][m][n] = __builtin_amdgcn_mfma_f32_16x16x32_bf16(Bt[n][k], At[m][k], acc[ai][bj][m][n], 0, 0, 0); __builtin_amdgcn_s_setprio(0); } while (0)
; #define PG8_WAIT_V(n) asm volatile("s_waitcnt vmcnt(" #n ")" ::: "memory")
; #define PG8_WAIT_L(n) asm volatile("s_waitcnt lgkmcnt(" #n ")" ::: "memory")
; #define PG8_BAR __builtin_amdgcn_s_barrier()
; #define PG8_SCHED __builtin_amdgcn_sched_barrier(0)
; template <class Epi>
; __device__ __forceinline__ void gemm_phase(const Tb tb, LAS unsigned char* lds, const Gemm g, const StaticOrder& S, const Epi& E) {
;     ...
;             PG8_WAIT_V(6); PG8_BAR; PG8_MMA(1, 1, At, B1); PG8_BAR;
;             PG8_LDB(B0, 1, 0); PG8_SCHED; PG8_LDA(At, 1, 0); PG8_STAGE(PG8_SA(0, 1), a2 + hstep, voffA);
;             PG8_WAIT_L(8); PG8_BAR; PG8_WAIT_L(0); PG8_MMA(0, 0, At, B0); PG8_BAR; PG8_SCHED;
;             PG8_LDB(B1, 1, 1); PG8_STAGE(PG8_SB(1, 0), b3, voffB);
;             PG8_BAR; PG8_WAIT_L(0); PG8_MMA(0, 1, At, B1); PG8_BAR;
;             PG8_LDA(At, 1, 1); PG8_STAGE(PG8_SA(1, 0), a3, voffA);
;             PG8_BAR; PG8_WAIT_L(0); PG8_MMA(1, 0, At, B0); PG8_BAR; PG8_SCHED;
	s_add_u32 s22, s24, 0xb0000
	s_addc_u32 s23, s25, 0
	s_add_i32 s52, s53, s35
	v_lshl_add_u64 v[134:135], s[22:23], 0, v[180:181]
	s_mov_b32 m0, s52
	s_nop 0
	global_load_lds_dwordx4 v[134:135], off
	v_lshl_add_u64 v[134:135], s[22:23], 0, v[128:129]
	s_add_i32 m0, s52, 0x2000
	s_nop 0
	global_load_lds_dwordx4 v[134:135], off
	s_waitcnt vmcnt(6)
	s_barrier
	s_setprio 1
	v_mfma_f32_16x16x32_bf16 v[52:55], v[212:215], v[156:159], v[52:55]
	v_mfma_f32_16x16x32_bf16 v[48:51], v[220:223], v[156:159], v[48:51]
	v_mfma_f32_16x16x32_bf16 v[36:39], v[212:215], v[164:167], v[36:39]
	v_mfma_f32_16x16x32_bf16 v[32:35], v[220:223], v[164:167], v[32:35]
	v_mfma_f32_16x16x32_bf16 v[20:23], v[212:215], v[172:175], v[20:23]
	v_mfma_f32_16x16x32_bf16 v[16:19], v[220:223], v[172:175], v[16:19]
	v_mfma_f32_16x16x32_bf16 v[4:7], v[212:215], v[204:207], v[4:7]
	v_mfma_f32_16x16x32_bf16 v[0:3], v[220:223], v[204:207], v[0:3]
	v_mfma_f32_16x16x32_bf16 v[52:55], v[216:219], v[160:163], v[52:55]
	v_mfma_f32_16x16x32_bf16 v[48:51], v[224:227], v[160:163], v[48:51]
	v_mfma_f32_16x16x32_bf16 v[36:39], v[216:219], v[168:171], v[36:39]
	v_mfma_f32_16x16x32_bf16 v[32:35], v[224:227], v[168:171], v[32:35]
	v_mfma_f32_16x16x32_bf16 v[20:23], v[216:219], v[176:179], v[20:23]
	v_mfma_f32_16x16x32_bf16 v[16:19], v[224:227], v[176:179], v[16:19]
	v_mfma_f32_16x16x32_bf16 v[4:7], v[216:219], v[208:211], v[4:7]
	v_mfma_f32_16x16x32_bf16 v[0:3], v[224:227], v[208:211], v[0:3]
	s_setprio 0
	s_add_i32 s52, 0, 0x18000
	v_add_u32_e32 v146, s52, v153
	s_barrier
	ds_read_b128 v[134:137], v146
	ds_read_b128 v[138:141], v146 offset:1024
	ds_read_b128 v[142:145], v146 offset:2048
	ds_read_b128 v[146:149], v146 offset:3072
	s_add_u32 s22, s26, 0xb0000
	s_addc_u32 s23, s27, 0
	s_mov_b32 m0, s38
	v_lshl_add_u64 v[212:213], s[22:23], 0, v[180:181]
	ds_read_b128 v[156:159], v155 offset:32768
	ds_read_b128 v[160:163], v155 offset:33792
	ds_read_b128 v[164:167], v155 offset:34816
	ds_read_b128 v[168:171], v155 offset:35840
	ds_read_b128 v[172:175], v155 offset:36864
	ds_read_b128 v[176:179], v155 offset:37888
	ds_read_b128 v[204:207], v155 offset:38912
	ds_read_b128 v[208:211], v155 offset:39936
	global_load_lds_dwordx4 v[212:213], off
	v_lshl_add_u64 v[212:213], s[22:23], 0, v[128:129]
	s_mov_b32 m0, s39
	s_nop 0
	global_load_lds_dwordx4 v[212:213], off
	s_waitcnt lgkmcnt(8)
	s_barrier
	s_waitcnt lgkmcnt(0)
	s_setprio 1
	s_waitcnt lgkmcnt(0)
	v_mfma_f32_16x16x32_bf16 v[124:127], v[134:137], v[156:159], v[124:127]
	v_mfma_f32_16x16x32_bf16 v[120:123], v[142:145], v[156:159], v[120:123]
	v_mfma_f32_16x16x32_bf16 v[108:111], v[134:137], v[164:167], v[108:111]
	v_mfma_f32_16x16x32_bf16 v[104:107], v[142:145], v[164:167], v[104:107]
	v_mfma_f32_16x16x32_bf16 v[92:95], v[134:137], v[172:175], v[92:95]
	v_mfma_f32_16x16x32_bf16 v[88:91], v[142:145], v[172:175], v[88:91]
	v_mfma_f32_16x16x32_bf16 v[76:79], v[134:137], v[204:207], v[76:79]
	v_mfma_f32_16x16x32_bf16 v[72:75], v[142:145], v[204:207], v[72:75]
	v_mfma_f32_16x16x32_bf16 v[124:127], v[138:141], v[160:163], v[124:127]
	v_mfma_f32_16x16x32_bf16 v[120:123], v[146:149], v[160:163], v[120:123]
	v_mfma_f32_16x16x32_bf16 v[108:111], v[138:141], v[168:171], v[108:111]
	v_mfma_f32_16x16x32_bf16 v[104:107], v[146:149], v[168:171], v[104:107]
	v_mfma_f32_16x16x32_bf16 v[92:95], v[138:141], v[176:179], v[92:95]
	v_mfma_f32_16x16x32_bf16 v[88:91], v[146:149], v[176:179], v[88:91]
	v_mfma_f32_16x16x32_bf16 v[76:79], v[138:141], v[208:211], v[76:79]
	v_mfma_f32_16x16x32_bf16 v[72:75], v[146:149], v[208:211], v[72:75]
	s_setprio 0
	s_barrier
	s_add_i32 s26, 0, 0x1c000
	s_add_i32 s22, s52, s35
	v_add_u32_e32 v191, s26, v153
	v_lshl_add_u64 v[150:151], v[150:151], 0, s[0:1]
	s_mov_b32 m0, s22
	ds_read_b128 v[212:215], v191
	ds_read_b128 v[216:219], v191 offset:1024
	ds_read_b128 v[220:223], v191 offset:2048
	ds_read_b128 v[224:227], v191 offset:3072
	global_load_lds_dwordx4 v[150:151], off
	v_lshl_add_u64 v[150:151], v[198:199], 0, s[0:1]
	s_add_i32 m0, s22, 0x2000
	s_nop 0
	global_load_lds_dwordx4 v[150:151], off
	s_barrier
; #define PG8_STAGE(bufoff, gbase, voff) do { _Pragma("unroll") for (int _i = 0; _i < 2; ++_i) \
;         __builtin_amdgcn_global_load_lds((const unsigned*)((const char*)(gbase) + (voff)[_i]), (LAS unsigned*)(lds + (bufoff) + ldsw + _i * 8192), 16, 0, 0); } while (0)
; #define PG8_LDA(dst, b, h) do { _Pragma("unroll") for (int m = 0; m < 4; ++m) _Pragma("unroll") for (int k = 0; k < 2; ++k) dst[m][k] = *(const LAS bf16x8*)(lds + PG8_SA(b, h) + aoff + m * 2048 + k * 1024); } while (0)
; #define PG8_LDB(dst, b, h) do { _Pragma("unroll") for (int n = 0; n < 2; ++n) _Pragma("unroll") for (int k = 0; k < 2; ++k) dst[n][k] = *(const LAS bf16x8*)(lds + PG8_SB(b, h) + boff + n * 2048 + k * 1024); } while (0)
; #define PG8_MMA(ai, bj, At, Bt) do { __builtin_amdgcn_s_setprio(1); _Pragma("unroll") for (int m = 0; m < 4; ++m) _Pragma("unroll") for (int n = 0; n < 2; ++n) _Pragma("unroll") for (int k = 0; k < 2; ++k) \
;         acc[ai][bj][m][n] = __builtin_amdgcn_mfma_f32_16x16x32_bf16(Bt[n][k], At[m][k], acc[ai][bj][m][n], 0, 0, 0); __builtin_amdgcn_s_setprio(0); } while (0)
; #define PG8_WAIT_V(n) asm volatile("s_waitcnt vmcnt(" #n ")" ::: "memory")
; #define PG8_WAIT_L(n) asm volatile("s_waitcnt lgkmcnt(" #n ")" ::: "memory")
; template <class Epi>
; __device__ __forceinline__ void gemm_phase(const Tb tb, LAS unsigned char* lds, const Gemm g, const StaticOrder& S, const Epi& E) {
;     ...
;             PG8_WAIT_L(8); PG8_BAR; PG8_WAIT_L(0); PG8_MMA(0, 0, At, B0); PG8_BAR; PG8_SCHED;
;             PG8_LDB(B1, 1, 1); PG8_STAGE(PG8_SB(1, 0), b3, voffB);
;             PG8_BAR; PG8_WAIT_L(0); PG8_MMA(0, 1, At, B1); PG8_BAR;
;             PG8_LDA(At, 1, 1); PG8_STAGE(PG8_SA(1, 0), a3, voffA);
;             PG8_BAR; PG8_WAIT_L(0); PG8_MMA(1, 0, At, B0); PG8_BAR; PG8_SCHED;
;             PG8_STAGE(PG8_SB(1, 1), b3 + hstep, voffB);
;             PG8_WAIT_V(6); PG8_BAR; PG8_MMA(1, 1, At, B1); PG8_BAR;
;         }
;     __device__ __forceinline__ void operator()(const f32x4 (&acc)[2][2][4][2], const pg8::Unit& u, int wr, int wc, int fr, int fq) const {
;         const int row0 = u.pm * 256 + wr * 64 + fr, col0 = u.pn * 256 + wc * 32 + 4 * fq;
; #pragma unroll
;         for (int ai = 0; ai < 2; ++ai)
; #pragma unroll
;             for (int m = 0; m < 4; ++m) {
;                 const int row = row0 + ai * 128 + m * 16; float mu, rstd; row_stats(stats_prev, row, mu, rstd);
	s_waitcnt lgkmcnt(0)
	s_setprio 1
	s_waitcnt lgkmcnt(0)
	v_mfma_f32_16x16x32_bf16 v[116:119], v[212:215], v[156:159], v[116:119]
	v_mfma_f32_16x16x32_bf16 v[112:115], v[220:223], v[156:159], v[112:115]
	v_mfma_f32_16x16x32_bf16 v[100:103], v[212:215], v[164:167], v[100:103]
	v_mfma_f32_16x16x32_bf16 v[96:99], v[220:223], v[164:167], v[96:99]
	v_mfma_f32_16x16x32_bf16 v[84:87], v[212:215], v[172:175], v[84:87]
	v_mfma_f32_16x16x32_bf16 v[80:83], v[220:223], v[172:175], v[80:83]
	v_mfma_f32_16x16x32_bf16 v[68:71], v[212:215], v[204:207], v[68:71]
	v_mfma_f32_16x16x32_bf16 v[64:67], v[220:223], v[204:207], v[64:67]
	v_mfma_f32_16x16x32_bf16 v[116:119], v[216:219], v[160:163], v[116:119]
	v_mfma_f32_16x16x32_bf16 v[112:115], v[224:227], v[160:163], v[112:115]
	v_mfma_f32_16x16x32_bf16 v[100:103], v[216:219], v[168:171], v[100:103]
	v_mfma_f32_16x16x32_bf16 v[96:99], v[224:227], v[168:171], v[96:99]
	v_mfma_f32_16x16x32_bf16 v[84:87], v[216:219], v[176:179], v[84:87]
	v_mfma_f32_16x16x32_bf16 v[80:83], v[224:227], v[176:179], v[80:83]
	v_mfma_f32_16x16x32_bf16 v[68:71], v[216:219], v[208:211], v[68:71]
	v_mfma_f32_16x16x32_bf16 v[64:67], v[224:227], v[208:211], v[64:67]
	s_setprio 0
	s_mov_b32 m0, s40
	v_lshl_add_u64 v[150:151], v[228:229], 0, s[0:1]
	s_barrier
	ds_read_b128 v[156:159], v155 offset:49152
	ds_read_b128 v[160:163], v155 offset:50176
	ds_read_b128 v[164:167], v155 offset:51200
	ds_read_b128 v[168:171], v155 offset:52224
	ds_read_b128 v[172:175], v155 offset:53248
	ds_read_b128 v[176:179], v155 offset:54272
	ds_read_b128 v[204:207], v155 offset:55296
	ds_read_b128 v[208:211], v155 offset:56320
	global_load_lds_dwordx4 v[150:151], off
	v_lshl_add_u64 v[150:151], v[230:231], 0, s[0:1]
	s_mov_b32 m0, s41
	s_nop 0
	global_load_lds_dwordx4 v[150:151], off
	s_barrier
	s_waitcnt lgkmcnt(0)
	s_setprio 1
	s_waitcnt lgkmcnt(0)
	v_mfma_f32_16x16x32_bf16 v[60:63], v[134:137], v[156:159], v[60:63]
	v_mfma_f32_16x16x32_bf16 v[56:59], v[142:145], v[156:159], v[56:59]
	v_mfma_f32_16x16x32_bf16 v[44:47], v[134:137], v[164:167], v[44:47]
	v_mfma_f32_16x16x32_bf16 v[40:43], v[142:145], v[164:167], v[40:43]
	v_mfma_f32_16x16x32_bf16 v[28:31], v[134:137], v[172:175], v[28:31]
	v_mfma_f32_16x16x32_bf16 v[24:27], v[142:145], v[172:175], v[24:27]
	v_mfma_f32_16x16x32_bf16 v[12:15], v[134:137], v[204:207], v[12:15]
	v_mfma_f32_16x16x32_bf16 v[8:11], v[142:145], v[204:207], v[8:11]
	v_mfma_f32_16x16x32_bf16 v[60:63], v[138:141], v[160:163], v[60:63]
	v_mfma_f32_16x16x32_bf16 v[56:59], v[146:149], v[160:163], v[56:59]
	v_mfma_f32_16x16x32_bf16 v[44:47], v[138:141], v[168:171], v[44:47]
	v_mfma_f32_16x16x32_bf16 v[40:43], v[146:149], v[168:171], v[40:43]
	v_mfma_f32_16x16x32_bf16 v[28:31], v[138:141], v[176:179], v[28:31]
	v_mfma_f32_16x16x32_bf16 v[24:27], v[146:149], v[176:179], v[24:27]
	v_mfma_f32_16x16x32_bf16 v[12:15], v[138:141], v[208:211], v[12:15]
	v_mfma_f32_16x16x32_bf16 v[8:11], v[146:149], v[208:211], v[8:11]
	s_setprio 0
	s_barrier
	s_add_u32 s22, s24, 0xb0080
	s_addc_u32 s23, s25, 0
	s_add_i32 s24, s26, s35
	v_lshl_add_u64 v[134:135], s[22:23], 0, v[180:181]
	s_mov_b32 m0, s24
	s_nop 0
	global_load_lds_dwordx4 v[134:135], off
	v_lshl_add_u64 v[134:135], s[22:23], 0, v[128:129]
	s_add_i32 m0, s24, 0x2000
	s_nop 0
	global_load_lds_dwordx4 v[134:135], off
	s_waitcnt vmcnt(6)
	s_barrier
	s_setprio 1
	v_mfma_f32_16x16x32_bf16 v[52:55], v[212:215], v[156:159], v[52:55]
	v_mfma_f32_16x16x32_bf16 v[48:51], v[220:223], v[156:159], v[48:51]
	v_mfma_f32_16x16x32_bf16 v[36:39], v[212:215], v[164:167], v[36:39]
	v_mfma_f32_16x16x32_bf16 v[32:35], v[220:223], v[164:167], v[32:35]
	v_mfma_f32_16x16x32_bf16 v[20:23], v[212:215], v[172:175], v[20:23]
	v_mfma_f32_16x16x32_bf16 v[16:19], v[220:223], v[172:175], v[16:19]
	v_mfma_f32_16x16x32_bf16 v[4:7], v[212:215], v[204:207], v[4:7]
	v_mfma_f32_16x16x32_bf16 v[0:3], v[220:223], v[204:207], v[0:3]
	v_mfma_f32_16x16x32_bf16 v[52:55], v[216:219], v[160:163], v[52:55]
	v_mfma_f32_16x16x32_bf16 v[48:51], v[224:227], v[160:163], v[48:51]
	v_mfma_f32_16x16x32_bf16 v[36:39], v[216:219], v[168:171], v[36:39]
	v_mfma_f32_16x16x32_bf16 v[32:35], v[224:227], v[168:171], v[32:35]
	v_mfma_f32_16x16x32_bf16 v[20:23], v[216:219], v[176:179], v[20:23]
	v_mfma_f32_16x16x32_bf16 v[16:19], v[224:227], v[176:179], v[16:19]
	v_mfma_f32_16x16x32_bf16 v[4:7], v[216:219], v[208:211], v[4:7]
	v_mfma_f32_16x16x32_bf16 v[0:3], v[224:227], v[208:211], v[0:3]
	s_setprio 0
	s_add_i32 s51, s51, 2
	s_add_u32 s49, s49, 0x100
	s_addc_u32 s50, s50, 0
	s_cmp_gt_u32 s51, 41
	s_mov_b64 s[22:23], s[6:7]
	s_barrier
	s_cbranch_scc0 .LBB0_1465
	v_lshl_add_u32 v140, s48, 8, v152
	v_cndmask_b32_e64 v134, 0, 1, s[18:19]
	v_cmp_ne_u32_e64 s[6:7], 1, v134
	s_andn2_b64 vcc, exec, s[18:19]
	v_ashrrev_i32_e32 v141, 31, v140
	s_cbranch_vccnz .LBB0_1468
	v_lshl_add_u64 v[134:135], v[140:141], 3, s[10:11]
	global_load_dwordx2 v[144:145], v[134:135], off
	global_load_dwordx2 v[226:227], v[134:135], off offset:128
	global_load_dwordx2 v[232:233], v[134:135], off offset:256
	global_load_dwordx2 v[234:235], v[134:135], off offset:384
	global_load_dwordx2 v[242:243], v[134:135], off offset:1024
	global_load_dwordx2 v[244:245], v[134:135], off offset:1152
	global_load_dwordx2 v[250:251], v[134:135], off offset:1280
	s_waitcnt vmcnt(0)
	v_mov_b32_e32 v146, v145
	s_branch .LBB0_1469

; __device__ __forceinline__ void row_stats(const float* mur, int row, float& mu, float& rstd) {
;     if (mur) { const float2 v = *(const float2*)(mur + 2 * (size_t)row); mu = v.x; rstd = v.y; }
;     else { mu = 0.f; rstd = 1.f; }
;     __device__ __forceinline__ void operator()(const f32x4 (&acc)[2][2][4][2], const pg8::Unit& u, int wr, int wc, int fr, int fq) const {
;     ...
;                 const int row = row0 + ai * 128 + m * 16; float mu, rstd; row_stats(stats_prev, row, mu, rstd);
.LBB0_1479:
	s_or_b64 exec, exec, s[24:25]
	v_or_b32_e32 v112, 16, v140
	s_and_b64 vcc, exec, s[6:7]
	v_ashrrev_i32_e32 v113, 31, v112
	s_cbranch_vccnz .LBB0_1481
	s_waitcnt lgkmcnt(0)
	v_mov_b32_e32 v116, v226
	v_mov_b32_e32 v117, v227
	v_mov_b32_e32 v118, v117
	s_branch .LBB0_1482

; __device__ __forceinline__ void row_stats(const float* mur, int row, float& mu, float& rstd) {
;     if (mur) { const float2 v = *(const float2*)(mur + 2 * (size_t)row); mu = v.x; rstd = v.y; }
;     else { mu = 0.f; rstd = 1.f; }
;     __device__ __forceinline__ void operator()(const f32x4 (&acc)[2][2][4][2], const pg8::Unit& u, int wr, int wc, int fr, int fq) const {
;     ...
;                 const int row = row0 + ai * 128 + m * 16; float mu, rstd; row_stats(stats_prev, row, mu, rstd);
.LBB0_1492:
	s_or_b64 exec, exec, s[24:25]
	v_or_b32_e32 v96, 32, v140
	s_and_b64 vcc, exec, s[6:7]
	v_ashrrev_i32_e32 v97, 31, v96
	s_cbranch_vccnz .LBB0_1494
	s_waitcnt lgkmcnt(0)
	v_mov_b32_e32 v100, v232
	v_mov_b32_e32 v101, v233
	v_mov_b32_e32 v102, v101
	s_branch .LBB0_1495

; __device__ __forceinline__ void row_stats(const float* mur, int row, float& mu, float& rstd) {
;     if (mur) { const float2 v = *(const float2*)(mur + 2 * (size_t)row); mu = v.x; rstd = v.y; }
;     else { mu = 0.f; rstd = 1.f; }
;     __device__ __forceinline__ void operator()(const f32x4 (&acc)[2][2][4][2], const pg8::Unit& u, int wr, int wc, int fr, int fq) const {
;     ...
;                 const int row = row0 + ai * 128 + m * 16; float mu, rstd; row_stats(stats_prev, row, mu, rstd);
.LBB0_1505:
	s_or_b64 exec, exec, s[24:25]
	v_or_b32_e32 v80, 48, v140
	s_and_b64 vcc, exec, s[6:7]
	v_ashrrev_i32_e32 v81, 31, v80
	s_cbranch_vccnz .LBB0_1507
	s_waitcnt lgkmcnt(0)
	v_mov_b32_e32 v84, v234
	v_mov_b32_e32 v85, v235
	v_mov_b32_e32 v86, v85
	s_branch .LBB0_1508

; __device__ __forceinline__ void row_stats(const float* mur, int row, float& mu, float& rstd) {
;     if (mur) { const float2 v = *(const float2*)(mur + 2 * (size_t)row); mu = v.x; rstd = v.y; }
;     else { mu = 0.f; rstd = 1.f; }
;     __device__ __forceinline__ void operator()(const f32x4 (&acc)[2][2][4][2], const pg8::Unit& u, int wr, int wc, int fr, int fq) const {
;     ...
;                 const int row = row0 + ai * 128 + m * 16; float mu, rstd; row_stats(stats_prev, row, mu, rstd);
.LBB0_1518:
	s_or_b64 exec, exec, s[24:25]
	v_add_u32_e32 v64, 0x80, v140
	s_and_b64 vcc, exec, s[6:7]
	v_ashrrev_i32_e32 v65, 31, v64
	s_cbranch_vccnz .LBB0_1520
	s_waitcnt lgkmcnt(0)
	v_mov_b32_e32 v68, v242
	v_mov_b32_e32 v69, v243
	v_mov_b32_e32 v70, v69
	s_branch .LBB0_1521

; __device__ __forceinline__ void row_stats(const float* mur, int row, float& mu, float& rstd) {
;     if (mur) { const float2 v = *(const float2*)(mur + 2 * (size_t)row); mu = v.x; rstd = v.y; }
;     else { mu = 0.f; rstd = 1.f; }
;     __device__ __forceinline__ void operator()(const f32x4 (&acc)[2][2][4][2], const pg8::Unit& u, int wr, int wc, int fr, int fq) const {
;     ...
;                 const int row = row0 + ai * 128 + m * 16; float mu, rstd; row_stats(stats_prev, row, mu, rstd);
.LBB0_1531:
	s_or_b64 exec, exec, s[24:25]
	v_add_u32_e32 v48, 0x90, v140
	s_and_b64 vcc, exec, s[6:7]
	v_ashrrev_i32_e32 v49, 31, v48
	s_cbranch_vccnz .LBB0_1533
	s_waitcnt lgkmcnt(0)
	v_mov_b32_e32 v52, v244
	v_mov_b32_e32 v53, v245
	v_mov_b32_e32 v54, v53
	s_branch .LBB0_1534

; __device__ __forceinline__ void row_stats(const float* mur, int row, float& mu, float& rstd) {
;     if (mur) { const float2 v = *(const float2*)(mur + 2 * (size_t)row); mu = v.x; rstd = v.y; }
;     else { mu = 0.f; rstd = 1.f; }
;     __device__ __forceinline__ void operator()(const f32x4 (&acc)[2][2][4][2], const pg8::Unit& u, int wr, int wc, int fr, int fq) const {
;     ...
;                 const int row = row0 + ai * 128 + m * 16; float mu, rstd; row_stats(stats_prev, row, mu, rstd);
.LBB0_1544:
	s_or_b64 exec, exec, s[24:25]
	v_add_u32_e32 v32, 0xa0, v140
	s_and_b64 vcc, exec, s[6:7]
	v_ashrrev_i32_e32 v33, 31, v32
	s_cbranch_vccnz .LBB0_1546
	s_waitcnt lgkmcnt(0)
	v_mov_b32_e32 v36, v250
	v_mov_b32_e32 v37, v251
	v_mov_b32_e32 v38, v37
	s_branch .LBB0_1547

; __device__ __forceinline__ void pro_part(ArgsRef a, const Tb tb, int l, int part, int vb, int VG, LAS unsigned char* lds) {
;     ...
;             const int wv = tb.tid >> 6, lane = tb.tid & 63;
;             float* wg8 = (float*)(ws + OFF_WG8);
;             const float* W = a.in[7] + (size_t)l * D_ * NIN_;
;             float s1 = 0.f, s2 = 0.f;
;             for (int k = lane; k < D_; k += 64) { const float w = W[(size_t)k * NIN_ + NING_ + wv]; const float wgv = w * g_mix[k]; wg8[wv * 1024 + k] = wgv; s1 += wgv; s2 += b_mix[k] * w; }
.LBB0_1639:
	v_mov_b64_e32 v[16:17], v[10:11]
	global_load_dword v20, v[16:17], off
	global_load_dword v36, v[8:9], off
	global_load_dword v52, v[6:7], off
	v_lshl_add_u64 v[16:17], v[16:17], 0, s[10:11]
	global_load_dword v21, v[16:17], off
	global_load_dword v37, v[8:9], off offset:256
	global_load_dword v53, v[6:7], off offset:256
	v_lshl_add_u64 v[16:17], v[16:17], 0, s[10:11]
	global_load_dword v22, v[16:17], off
	global_load_dword v38, v[8:9], off offset:512
	global_load_dword v54, v[6:7], off offset:512
	v_lshl_add_u64 v[16:17], v[16:17], 0, s[10:11]
	global_load_dword v23, v[16:17], off
	global_load_dword v39, v[8:9], off offset:768
	global_load_dword v55, v[6:7], off offset:768
	v_lshl_add_u64 v[16:17], v[16:17], 0, s[10:11]
	global_load_dword v24, v[16:17], off
	global_load_dword v40, v[8:9], off offset:1024
	global_load_dword v56, v[6:7], off offset:1024
	v_lshl_add_u64 v[16:17], v[16:17], 0, s[10:11]
	global_load_dword v25, v[16:17], off
	global_load_dword v41, v[8:9], off offset:1280
	global_load_dword v57, v[6:7], off offset:1280
	v_lshl_add_u64 v[16:17], v[16:17], 0, s[10:11]
	global_load_dword v26, v[16:17], off
	global_load_dword v42, v[8:9], off offset:1536
	global_load_dword v58, v[6:7], off offset:1536
	v_lshl_add_u64 v[16:17], v[16:17], 0, s[10:11]
	global_load_dword v27, v[16:17], off
	global_load_dword v43, v[8:9], off offset:1792
	global_load_dword v59, v[6:7], off offset:1792
	v_lshl_add_u64 v[16:17], v[16:17], 0, s[10:11]
	global_load_dword v28, v[16:17], off
	global_load_dword v44, v[8:9], off offset:2048
	global_load_dword v60, v[6:7], off offset:2048
	v_lshl_add_u64 v[16:17], v[16:17], 0, s[10:11]
	global_load_dword v29, v[16:17], off
	global_load_dword v45, v[8:9], off offset:2304
	global_load_dword v61, v[6:7], off offset:2304
	v_lshl_add_u64 v[16:17], v[16:17], 0, s[10:11]
	global_load_dword v30, v[16:17], off
	global_load_dword v46, v[8:9], off offset:2560
	global_load_dword v62, v[6:7], off offset:2560
	v_lshl_add_u64 v[16:17], v[16:17], 0, s[10:11]
	global_load_dword v31, v[16:17], off
	global_load_dword v47, v[8:9], off offset:2816
	global_load_dword v63, v[6:7], off offset:2816
	v_lshl_add_u64 v[16:17], v[16:17], 0, s[10:11]
	global_load_dword v32, v[16:17], off
	global_load_dword v48, v[8:9], off offset:3072
	global_load_dword v64, v[6:7], off offset:3072
	v_lshl_add_u64 v[16:17], v[16:17], 0, s[10:11]
	global_load_dword v33, v[16:17], off
	global_load_dword v49, v[8:9], off offset:3328
	global_load_dword v65, v[6:7], off offset:3328
	v_lshl_add_u64 v[16:17], v[16:17], 0, s[10:11]
	global_load_dword v34, v[16:17], off
	global_load_dword v50, v[8:9], off offset:3584
	global_load_dword v66, v[6:7], off offset:3584
	v_lshl_add_u64 v[16:17], v[16:17], 0, s[10:11]
	global_load_dword v35, v[16:17], off
	global_load_dword v51, v[8:9], off offset:3840
	global_load_dword v67, v[6:7], off offset:3840
	s_waitcnt vmcnt(0)
; __device__ __forceinline__ void pro_part(ArgsRef a, const Tb tb, int l, int part, int vb, int VG, LAS unsigned char* lds) {
;     ...
;             for (int k = lane; k < D_; k += 64) { const float w = W[(size_t)k * NIN_ + NING_ + wv]; const float wgv = w * g_mix[k]; wg8[wv * 1024 + k] = wgv; s1 += wgv; s2 += b_mix[k] * w; }
;             s1 = wave_sum(s1); s2 = wave_sum(s2);
;             if (lane == 0) { wg8[8192 + wv] = s1; wg8[8192 + 8 + wv] = s2; }
	v_mul_f32_e32 v36, v20, v36
	global_store_dword v[4:5], v36, off
	v_mul_f32_e32 v52, v20, v52
	v_add_f32_e32 v2, v2, v36
	v_add_f32_e32 v3, v3, v52
	v_mul_f32_e32 v37, v21, v37
	global_store_dword v[4:5], v37, off offset:256
	v_mul_f32_e32 v53, v21, v53
	v_add_f32_e32 v2, v2, v37
	v_add_f32_e32 v3, v3, v53
	v_mul_f32_e32 v38, v22, v38
	global_store_dword v[4:5], v38, off offset:512
	v_mul_f32_e32 v54, v22, v54
	v_add_f32_e32 v2, v2, v38
	v_add_f32_e32 v3, v3, v54
	v_mul_f32_e32 v39, v23, v39
	global_store_dword v[4:5], v39, off offset:768
	v_mul_f32_e32 v55, v23, v55
	v_add_f32_e32 v2, v2, v39
	v_add_f32_e32 v3, v3, v55
	v_mul_f32_e32 v40, v24, v40
	global_store_dword v[4:5], v40, off offset:1024
	v_mul_f32_e32 v56, v24, v56
	v_add_f32_e32 v2, v2, v40
	v_add_f32_e32 v3, v3, v56
	v_mul_f32_e32 v41, v25, v41
	global_store_dword v[4:5], v41, off offset:1280
	v_mul_f32_e32 v57, v25, v57
	v_add_f32_e32 v2, v2, v41
	v_add_f32_e32 v3, v3, v57
	v_mul_f32_e32 v42, v26, v42
	global_store_dword v[4:5], v42, off offset:1536
	v_mul_f32_e32 v58, v26, v58
	v_add_f32_e32 v2, v2, v42
	v_add_f32_e32 v3, v3, v58
	v_mul_f32_e32 v43, v27, v43
	global_store_dword v[4:5], v43, off offset:1792
	v_mul_f32_e32 v59, v27, v59
	v_add_f32_e32 v2, v2, v43
	v_add_f32_e32 v3, v3, v59
	v_mul_f32_e32 v44, v28, v44
	global_store_dword v[4:5], v44, off offset:2048
	v_mul_f32_e32 v60, v28, v60
	v_add_f32_e32 v2, v2, v44
	v_add_f32_e32 v3, v3, v60
	v_mul_f32_e32 v45, v29, v45
	global_store_dword v[4:5], v45, off offset:2304
	v_mul_f32_e32 v61, v29, v61
	v_add_f32_e32 v2, v2, v45
	v_add_f32_e32 v3, v3, v61
	v_mul_f32_e32 v46, v30, v46
	global_store_dword v[4:5], v46, off offset:2560
	v_mul_f32_e32 v62, v30, v62
	v_add_f32_e32 v2, v2, v46
	v_add_f32_e32 v3, v3, v62
	v_mul_f32_e32 v47, v31, v47
	global_store_dword v[4:5], v47, off offset:2816
	v_mul_f32_e32 v63, v31, v63
	v_add_f32_e32 v2, v2, v47
	v_add_f32_e32 v3, v3, v63
	v_mul_f32_e32 v48, v32, v48
	global_store_dword v[4:5], v48, off offset:3072
	v_mul_f32_e32 v64, v32, v64
	v_add_f32_e32 v2, v2, v48
	v_add_f32_e32 v3, v3, v64
	v_mul_f32_e32 v49, v33, v49
	global_store_dword v[4:5], v49, off offset:3328
	v_mul_f32_e32 v65, v33, v65
	v_add_f32_e32 v2, v2, v49
	v_add_f32_e32 v3, v3, v65
	v_mul_f32_e32 v50, v34, v50
	global_store_dword v[4:5], v50, off offset:3584
	v_mul_f32_e32 v66, v34, v66
	v_add_f32_e32 v2, v2, v50
	v_add_f32_e32 v3, v3, v66
	v_mul_f32_e32 v51, v35, v51
	global_store_dword v[4:5], v51, off offset:3840
	v_mul_f32_e32 v67, v35, v67
	v_add_f32_e32 v2, v2, v51
	v_add_f32_e32 v3, v3, v67
	s_or_b64 exec, exec, s[4:5]
	v_cmp_lt_i32_e32 vcc, v237, v239
	v_xor_b32_e32 v8, 8, v236
	s_nop 0
	v_cndmask_b32_e32 v4, v236, v237, vcc
	v_lshlrev_b32_e32 v4, 2, v4
	ds_bpermute_b32 v5, v4, v2
	v_cmp_lt_i32_e32 vcc, v240, v239
	ds_bpermute_b32 v4, v4, v3
	s_waitcnt lgkmcnt(1)
	v_add_f32_e32 v2, v2, v5
	v_cndmask_b32_e32 v6, v236, v240, vcc
	v_lshlrev_b32_e32 v6, 2, v6
	ds_bpermute_b32 v5, v6, v2
	v_cmp_lt_i32_e32 vcc, v241, v239
	s_waitcnt lgkmcnt(1)
	v_add_f32_e32 v3, v3, v4
	ds_bpermute_b32 v4, v6, v3
	v_cndmask_b32_e32 v7, v236, v241, vcc
	v_lshlrev_b32_e32 v7, 2, v7
	s_waitcnt lgkmcnt(1)
	v_add_f32_e32 v2, v2, v5
	ds_bpermute_b32 v5, v7, v2
	v_cmp_lt_i32_e32 vcc, v8, v239
	s_waitcnt lgkmcnt(1)
	v_add_f32_e32 v3, v3, v4
	ds_bpermute_b32 v4, v7, v3
	v_cndmask_b32_e32 v8, v236, v8, vcc
	v_lshlrev_b32_e32 v8, 2, v8
	s_waitcnt lgkmcnt(1)
	v_add_f32_e32 v2, v2, v5
	ds_bpermute_b32 v5, v8, v2
	v_xor_b32_e32 v6, 16, v236
	s_waitcnt lgkmcnt(1)
	v_add_f32_e32 v3, v3, v4
	v_cmp_lt_i32_e32 vcc, v6, v239
	ds_bpermute_b32 v4, v8, v3
	s_waitcnt lgkmcnt(1)
	v_add_f32_e32 v2, v2, v5
	v_cndmask_b32_e32 v5, v236, v6, vcc
	v_lshlrev_b32_e32 v5, 2, v5
	ds_bpermute_b32 v6, v5, v2
	s_waitcnt lgkmcnt(1)
	v_add_f32_e32 v4, v3, v4
	ds_bpermute_b32 v5, v5, v4
	s_waitcnt lgkmcnt(1)
	v_add_f32_e32 v2, v2, v6
	v_xor_b32_e32 v6, 32, v236
	v_cmp_lt_i32_e32 vcc, v6, v239
	s_waitcnt lgkmcnt(0)
	v_add_f32_e32 v4, v4, v5
	v_cndmask_b32_e32 v3, v236, v6, vcc
	v_lshlrev_b32_e32 v6, 2, v3
	ds_bpermute_b32 v3, v6, v2
	ds_bpermute_b32 v5, v6, v4
	v_cmp_eq_u32_e32 vcc, 0, v12
	s_and_saveexec_b64 s[4:5], vcc
	s_cbranch_execz .LBB0_1642
	v_lshl_add_u64 v[0:1], v[0:1], 2, s[2:3]
	v_add_co_u32_e32 v0, vcc, 0x8000, v0
	s_waitcnt lgkmcnt(1)
	v_add_f32_e32 v2, v2, v3
	v_addc_co_u32_e32 v1, vcc, 0, v1, vcc
	s_waitcnt lgkmcnt(0)
	v_add_f32_e32 v4, v4, v5
	global_store_dword v[0:1], v2, off
	global_store_dword v[0:1], v4, off offset:32

; __device__ __forceinline__ unsigned pk2(float lo, float hi) { const f32x2_t v = {lo, hi}; const bf16x2_t b = __builtin_convertvector(v, bf16x2_t); return __builtin_bit_cast(unsigned, b); }
; __device__ __forceinline__ void pro_part(ArgsRef a, const Tb tb, int l, int part, int vb, int VG, LAS unsigned char* lds) {
;     ...
;         if (l == 0) {
;             const size_t gt = (size_t)vb * 512 + tb.tid, GT = (size_t)VG * 512;
;             const f32x4* x4 = (const f32x4*)a.in[0]; u32x2* yb = (u32x2*)(ws + OFF_YB);
;             for (size_t i = gt; i < (size_t)T_ * D_ / 4; i += GT) { const f32x4 v = __builtin_nontemporal_load(x4 + i); u32x2 w; w.x = pk2(v[0], v[1]); w.y = pk2(v[2], v[3]); yb[i] = w; }
;         }
.LBB0_1643:
	s_ashr_i32 s69, s68, 31
	s_lshl_b64 s[2:3], s[68:69], 9
	v_ashrrev_i32_e32 v197, 31, v196
	s_waitcnt vmcnt(0) lgkmcnt(0)
	v_lshl_add_u64 v[0:1], s[2:3], 0, v[196:197]
	s_mov_b64 s[2:3], 0x400000
	v_cmp_gt_u64_e32 vcc, s[2:3], v[0:1]
	s_and_saveexec_b64 s[2:3], vcc
	s_cbranch_execz .LBB0_1646
	v_readlane_b32 s6, v254, 19
	s_ashr_i32 s57, s56, 31
	v_readlane_b32 s7, v254, 20
	s_lshl_b64 s[4:5], s[56:57], 9
	s_load_dwordx2 s[8:9], s[6:7], 0x0
	s_lshl_b64 s[6:7], s[68:69], 12
	s_add_u32 s6, s48, s6
	s_addc_u32 s7, s49, s7
	v_lshl_add_u64 v[2:3], v[196:197], 3, s[6:7]
	s_mov_b64 s[6:7], 0x376a100
	v_lshl_add_u64 v[2:3], v[2:3], 0, s[6:7]
	s_lshl_b64 s[6:7], s[56:57], 12
	s_lshl_b64 s[10:11], s[68:69], 13
	s_waitcnt lgkmcnt(0)
	s_add_u32 s8, s8, s10
	s_addc_u32 s9, s9, s11
	v_lshl_add_u64 v[4:5], v[196:197], 4, s[8:9]
	s_lshl_b64 s[8:9], s[56:57], 13
	s_mov_b64 s[10:11], 0
	s_cmpk_lg_u32 s56, 0x100
	s_cbranch_scc1 .LBB0_1645
	s_mov_b32 s12, 4
.Lxc_loop:
	global_load_dwordx4 v[8:11], v[4:5], off nt
	v_lshl_add_u64 v[6:7], v[4:5], 0, s[8:9]
	global_load_dwordx4 v[12:15], v[6:7], off nt
	v_lshl_add_u64 v[6:7], v[6:7], 0, s[8:9]
	global_load_dwordx4 v[16:19], v[6:7], off nt
	v_lshl_add_u64 v[6:7], v[6:7], 0, s[8:9]
	global_load_dwordx4 v[20:23], v[6:7], off nt
	v_lshl_add_u64 v[6:7], v[6:7], 0, s[8:9]
	global_load_dwordx4 v[24:27], v[6:7], off nt
	v_lshl_add_u64 v[6:7], v[6:7], 0, s[8:9]
	global_load_dwordx4 v[28:31], v[6:7], off nt
	v_lshl_add_u64 v[6:7], v[6:7], 0, s[8:9]
	global_load_dwordx4 v[32:35], v[6:7], off nt
	v_lshl_add_u64 v[6:7], v[6:7], 0, s[8:9]
	global_load_dwordx4 v[36:39], v[6:7], off nt
	v_lshl_add_u64 v[4:5], v[6:7], 0, s[8:9]
	s_waitcnt vmcnt(7)
	v_cvt_pk_bf16_f32 v8, v8, v9
	v_cvt_pk_bf16_f32 v9, v10, v11
	global_store_dwordx2 v[2:3], v[8:9], off
	v_lshl_add_u64 v[2:3], v[2:3], 0, s[6:7]
	s_waitcnt vmcnt(7)
	v_cvt_pk_bf16_f32 v12, v12, v13
	v_cvt_pk_bf16_f32 v13, v14, v15
	global_store_dwordx2 v[2:3], v[12:13], off
	v_lshl_add_u64 v[2:3], v[2:3], 0, s[6:7]
	s_waitcnt vmcnt(7)
	v_cvt_pk_bf16_f32 v16, v16, v17
	v_cvt_pk_bf16_f32 v17, v18, v19
	global_store_dwordx2 v[2:3], v[16:17], off
	v_lshl_add_u64 v[2:3], v[2:3], 0, s[6:7]
	s_waitcnt vmcnt(7)
	v_cvt_pk_bf16_f32 v20, v20, v21
	v_cvt_pk_bf16_f32 v21, v22, v23
	global_store_dwordx2 v[2:3], v[20:21], off
	v_lshl_add_u64 v[2:3], v[2:3], 0, s[6:7]
	s_waitcnt vmcnt(7)
	v_cvt_pk_bf16_f32 v24, v24, v25
	v_cvt_pk_bf16_f32 v25, v26, v27
	global_store_dwordx2 v[2:3], v[24:25], off
	v_lshl_add_u64 v[2:3], v[2:3], 0, s[6:7]
	s_waitcnt vmcnt(7)
	v_cvt_pk_bf16_f32 v28, v28, v29
	v_cvt_pk_bf16_f32 v29, v30, v31
	global_store_dwordx2 v[2:3], v[28:29], off
	v_lshl_add_u64 v[2:3], v[2:3], 0, s[6:7]
	s_waitcnt vmcnt(7)
	v_cvt_pk_bf16_f32 v32, v32, v33
	v_cvt_pk_bf16_f32 v33, v34, v35
	global_store_dwordx2 v[2:3], v[32:33], off
	v_lshl_add_u64 v[2:3], v[2:3], 0, s[6:7]
	s_waitcnt vmcnt(7)
	v_cvt_pk_bf16_f32 v36, v36, v37
	v_cvt_pk_bf16_f32 v37, v38, v39
	global_store_dwordx2 v[2:3], v[36:37], off
	v_lshl_add_u64 v[2:3], v[2:3], 0, s[6:7]
	s_sub_i32 s12, s12, 1
	s_cmp_lg_u32 s12, 0
	s_cbranch_scc1 .Lxc_loop
	s_branch .LBB0_1646

; __device__ __forceinline__ float bflo(unsigned w) { return __uint_as_float(w << 16); }
; __device__ __forceinline__ float bfhi(unsigned w) { return __uint_as_float(w & 0xffff0000u); }
; __device__ __forceinline__ void phase_final(ArgsRef a, const Tb tb) {
;     const float* part = (const float*)(a.ws + OFF_STATS) + (size_t)5 * T_ * 32;
;     const float* g = a.in[5] + 5 * D_; const float* bb = a.in[6] + 5 * D_;
;     const int wv = tb.tid >> 6, lane = tb.tid & 63;
;     const int gw = tb.bid * 8 + wv, GW = tb.G * 8;
;     for (int t = gw; t < T_; t += GW) {
;         float s = 0.f, q = 0.f;
;         if (lane < 8) { const f32x4 v = *(const f32x4*)(part + (size_t)t * 32 + lane * 4); s = v[0] + v[2]; q = v[1] + v[3]; }
;         s = wave_sum(s); q = wave_sum(q);
;         const float mu = s * (1.f / 1024.f), rstd = rsqrtf(fmaxf(q * (1.f / 1024.f) - mu * mu, 0.f) + LN_EPS_);
; #pragma unroll
;         for (int i = 0; i < 4; ++i) {
;             const int col = i * 256 + lane * 4;
;             const u32x2 rb = *(const u32x2*)((const bf16_t*)(a.ws + OFF_YB) + (size_t)t * D_ + col);
;             f32x4 y = (f32x4){bflo(rb.x), bfhi(rb.x), bflo(rb.y), bfhi(rb.y)};
;             const f32x4 g4 = *(const f32x4*)(g + col), b4 = *(const f32x4*)(bb + col);
.LBB0_1648:
	v_ashrrev_i32_e32 v16, 6, v196
	s_lshl_b32 s8, s68, 3
	v_add_u32_e32 v24, s8, v16
	s_movk_i32 s2, 0x4000
	v_cmp_gt_i32_e32 vcc, s2, v24
	s_and_saveexec_b64 s[4:5], vcc
	s_cbranch_execz .LBB0_1653
	v_readlane_b32 s2, v254, 19
	v_readlane_b32 s3, v254, 20
	s_load_dwordx4 s[12:15], s[2:3], 0x28
	s_load_dwordx2 s[16:17], s[2:3], 0x80
	v_cmp_lt_i32_e64 s[2:3], v237, v239
	s_lshl_b32 s6, s56, 3
	v_ashrrev_i32_e32 v17, 31, v16
	s_waitcnt vmcnt(0)
	v_cndmask_b32_e64 v0, v236, v237, s[2:3]
	v_cmp_lt_i32_e64 s[2:3], v240, v239
	v_lshlrev_b32_e32 v25, 2, v0
	s_waitcnt lgkmcnt(0)
	s_add_u32 s10, s14, 0x5000
	v_cndmask_b32_e64 v0, v236, v240, s[2:3]
	v_cmp_lt_i32_e64 s[2:3], v241, v239
	v_lshlrev_b32_e32 v26, 2, v0
	s_addc_u32 s11, s15, 0
	v_cndmask_b32_e64 v0, v236, v241, s[2:3]
	v_lshlrev_b32_e32 v27, 2, v0
	v_xor_b32_e32 v0, 8, v236
	v_cmp_lt_i32_e64 s[2:3], v0, v239
	s_add_u32 s12, s12, 0x5000
	s_addc_u32 s13, s13, 0
	v_cndmask_b32_e64 v0, v236, v0, s[2:3]
	v_lshlrev_b32_e32 v28, 2, v0
	v_xor_b32_e32 v0, 16, v236
	v_cmp_lt_i32_e64 s[2:3], v0, v239
	s_ashr_i32 s9, s8, 31
	v_lshl_add_u64 v[20:21], v[16:17], 0, s[8:9]
	v_cndmask_b32_e64 v0, v236, v0, s[2:3]
	v_lshlrev_b32_e32 v29, 2, v0
	v_xor_b32_e32 v0, 32, v236
	v_and_b32_e32 v22, 63, v196
	v_cmp_lt_i32_e64 s[2:3], v0, v239
	v_lshlrev_b64 v[16:17], 7, v[20:21]
	v_lshlrev_b64 v[18:19], 11, v[20:21]
	v_cndmask_b32_e64 v0, v236, v0, s[2:3]
	v_lshlrev_b32_e32 v180, 4, v22
	v_lshl_add_u64 v[16:17], s[48:49], 0, v[16:17]
	s_mov_b64 s[2:3], 0x3425040
	v_lshl_or_b32 v18, v22, 3, v18
	v_or_b32_e32 v6, 0x400, v180
	v_mov_b32_e32 v7, v181
	v_or_b32_e32 v10, 0x800, v180
	v_mov_b32_e32 v11, v181
	v_or_b32_e32 v14, 0xc00, v180
	v_mov_b32_e32 v15, v181
	v_lshl_add_u64 v[16:17], v[16:17], 0, s[2:3]
	s_ashr_i32 s7, s6, 31
	v_lshl_add_u64 v[18:19], s[48:49], 0, v[18:19]
	s_mov_b64 s[2:3], 0x376a500
	v_lshlrev_b64 v[20:21], 12, v[20:21]
	v_cmp_gt_u32_e32 vcc, 8, v22
	v_lshlrev_b32_e32 v30, 2, v0
	v_lshl_add_u64 v[0:1], s[12:13], 0, v[180:181]
	v_lshl_add_u64 v[2:3], s[10:11], 0, v[180:181]
	v_lshl_add_u64 v[4:5], s[12:13], 0, v[6:7]
	v_lshl_add_u64 v[6:7], s[10:11], 0, v[6:7]
	v_lshl_add_u64 v[8:9], s[12:13], 0, v[10:11]
	v_lshl_add_u64 v[10:11], s[10:11], 0, v[10:11]
	v_lshl_add_u64 v[12:13], s[12:13], 0, v[14:15]
	v_lshl_add_u64 v[14:15], s[10:11], 0, v[14:15]
	s_lshl_b64 s[8:9], s[6:7], 7
	v_lshl_add_u64 v[18:19], v[18:19], 0, s[2:3]
	s_lshl_b64 s[10:11], s[6:7], 11
	v_lshl_add_u64 v[20:21], s[16:17], 0, v[20:21]
	s_lshl_b64 s[12:13], s[6:7], 12
	s_mov_b64 s[14:15], 0
	global_load_dwordx4 v[48:51], v[0:1], off
	global_load_dwordx4 v[52:55], v[2:3], off
	global_load_dwordx4 v[56:59], v[4:5], off
	global_load_dwordx4 v[60:63], v[6:7], off
	global_load_dwordx4 v[64:67], v[8:9], off
	global_load_dwordx4 v[68:71], v[10:11], off
	global_load_dwordx4 v[72:75], v[12:13], off
	global_load_dwordx4 v[76:79], v[14:15], off
	s_branch .LBB0_1651
; __device__ __forceinline__ float bflo(unsigned w) { return __uint_as_float(w << 16); }
; __device__ __forceinline__ float bfhi(unsigned w) { return __uint_as_float(w & 0xffff0000u); }
; __device__ __forceinline__ void phase_final(ArgsRef a, const Tb tb) {
;     ...
;     for (int t = gw; t < T_; t += GW) {
;         float s = 0.f, q = 0.f;
;         if (lane < 8) { const f32x4 v = *(const f32x4*)(part + (size_t)t * 32 + lane * 4); s = v[0] + v[2]; q = v[1] + v[3]; }
;         s = wave_sum(s); q = wave_sum(q);
;         const float mu = s * (1.f / 1024.f), rstd = rsqrtf(fmaxf(q * (1.f / 1024.f) - mu * mu, 0.f) + LN_EPS_);
; #pragma unroll
;         for (int i = 0; i < 4; ++i) {
;             const int col = i * 256 + lane * 4;
;             const u32x2 rb = *(const u32x2*)((const bf16_t*)(a.ws + OFF_YB) + (size_t)t * D_ + col);
;             f32x4 y = (f32x4){bflo(rb.x), bfhi(rb.x), bflo(rb.y), bfhi(rb.y)};
;             const f32x4 g4 = *(const f32x4*)(g + col), b4 = *(const f32x4*)(bb + col);
;             y = (y - mu) * rstd * g4 + b4;
;             __builtin_nontemporal_store(y, (f32x4*)(a.out + (size_t)t * D_ + col));
;         }
.LBB0_1650:
	s_or_b64 exec, exec, s[2:3]
	global_load_dwordx2 v[40:41], v[18:19], off offset:-1024
	global_load_dwordx2 v[42:43], v[18:19], off offset:-512
	global_load_dwordx2 v[44:45], v[18:19], off
	global_load_dwordx2 v[46:47], v[18:19], off offset:512
	s_waitcnt vmcnt(4)
	v_pk_add_f32 v[22:23], v[32:33], v[34:35]
	s_nop 0
	ds_bpermute_b32 v36, v25, v22
	ds_bpermute_b32 v37, v25, v23
	s_waitcnt lgkmcnt(0)
	v_pk_add_f32 v[22:23], v[22:23], v[36:37]
	s_nop 0
	ds_bpermute_b32 v36, v26, v22
	ds_bpermute_b32 v37, v26, v23
	s_waitcnt lgkmcnt(0)
	v_pk_add_f32 v[22:23], v[22:23], v[36:37]
	s_nop 0
	ds_bpermute_b32 v36, v27, v22
	ds_bpermute_b32 v37, v27, v23
	s_waitcnt lgkmcnt(0)
	v_pk_add_f32 v[22:23], v[22:23], v[36:37]
	s_nop 0
	ds_bpermute_b32 v36, v28, v22
	ds_bpermute_b32 v37, v28, v23
	s_waitcnt lgkmcnt(0)
	v_pk_add_f32 v[22:23], v[22:23], v[36:37]
	s_nop 0
	ds_bpermute_b32 v36, v29, v22
	ds_bpermute_b32 v37, v29, v23
	s_waitcnt lgkmcnt(0)
	v_pk_add_f32 v[22:23], v[22:23], v[36:37]
	s_nop 0
	ds_bpermute_b32 v36, v30, v22
	ds_bpermute_b32 v37, v30, v23
	s_waitcnt lgkmcnt(0)
	v_pk_add_f32 v[22:23], v[22:23], v[36:37]
	v_lshl_add_u64 v[38:39], v[20:21], 0, v[180:181]
	v_mul_f32_e32 v22, 0x3a800000, v22
	v_mul_f32_e32 v23, 0x3a800000, v23
	v_fma_f32 v23, -v22, v22, v23
	v_max_f32_e32 v23, 0, v23
	v_add_f32_e32 v23, 0x3727c5ac, v23
	v_rsq_f32_e32 v23, v23
	v_add_u32_e32 v24, s6, v24
	v_lshl_add_u64 v[16:17], v[16:17], 0, s[8:9]
	v_lshl_add_u64 v[18:19], v[18:19], 0, s[10:11]
	v_lshl_add_u64 v[20:21], v[20:21], 0, s[12:13]
	v_cmp_lt_i32_e64 s[2:3], s61, v24
	s_or_b64 s[14:15], s[2:3], s[14:15]
	s_waitcnt vmcnt(0)
	v_lshlrev_b32_e32 v80, 16, v40
	v_and_b32_e32 v81, 0xffff0000, v40
	v_lshlrev_b32_e32 v82, 16, v41
	v_and_b32_e32 v83, 0xffff0000, v41
	v_sub_f32_e32 v80, v80, v22
	v_sub_f32_e32 v81, v81, v22
	v_sub_f32_e32 v82, v82, v22
	v_sub_f32_e32 v83, v83, v22
	v_mul_f32_e32 v80, v80, v23
	v_mul_f32_e32 v81, v81, v23
	v_mul_f32_e32 v82, v82, v23
	v_mul_f32_e32 v83, v83, v23
	v_fma_f32 v80, v48, v80, v52
	v_fma_f32 v81, v49, v81, v53
	v_fma_f32 v82, v50, v82, v54
	v_fma_f32 v83, v51, v83, v55
	global_store_dwordx4 v[38:39], v[80:83], off nt
	v_lshlrev_b32_e32 v84, 16, v42
	v_and_b32_e32 v85, 0xffff0000, v42
	v_lshlrev_b32_e32 v86, 16, v43
	v_and_b32_e32 v87, 0xffff0000, v43
	v_sub_f32_e32 v84, v84, v22
	v_sub_f32_e32 v85, v85, v22
	v_sub_f32_e32 v86, v86, v22
	v_sub_f32_e32 v87, v87, v22
	v_mul_f32_e32 v84, v84, v23
	v_mul_f32_e32 v85, v85, v23
	v_mul_f32_e32 v86, v86, v23
	v_mul_f32_e32 v87, v87, v23
	v_fma_f32 v84, v56, v84, v60
	v_fma_f32 v85, v57, v85, v61
	v_fma_f32 v86, v58, v86, v62
	v_fma_f32 v87, v59, v87, v63
	global_store_dwordx4 v[38:39], v[84:87], off offset:1024 nt
	v_lshlrev_b32_e32 v88, 16, v44
	v_and_b32_e32 v89, 0xffff0000, v44
	v_lshlrev_b32_e32 v90, 16, v45
	v_and_b32_e32 v91, 0xffff0000, v45
	v_sub_f32_e32 v88, v88, v22
	v_sub_f32_e32 v89, v89, v22
	v_sub_f32_e32 v90, v90, v22
	v_sub_f32_e32 v91, v91, v22
	v_mul_f32_e32 v88, v88, v23
	v_mul_f32_e32 v89, v89, v23
	v_mul_f32_e32 v90, v90, v23
	v_mul_f32_e32 v91, v91, v23
	v_fma_f32 v88, v64, v88, v68
	v_fma_f32 v89, v65, v89, v69
	v_fma_f32 v90, v66, v90, v70
	v_fma_f32 v91, v67, v91, v71
	global_store_dwordx4 v[38:39], v[88:91], off offset:2048 nt
	v_lshlrev_b32_e32 v92, 16, v46
	v_and_b32_e32 v93, 0xffff0000, v46
	v_lshlrev_b32_e32 v94, 16, v47
	v_and_b32_e32 v95, 0xffff0000, v47
	v_sub_f32_e32 v92, v92, v22
	v_sub_f32_e32 v93, v93, v22
	v_sub_f32_e32 v94, v94, v22
	v_sub_f32_e32 v95, v95, v22
	v_mul_f32_e32 v92, v92, v23
	v_mul_f32_e32 v93, v93, v23
	v_mul_f32_e32 v94, v94, v23
	v_mul_f32_e32 v95, v95, v23
	v_fma_f32 v92, v72, v92, v76
	v_fma_f32 v93, v73, v93, v77
	v_fma_f32 v94, v74, v94, v78
	v_fma_f32 v95, v75, v95, v79
	global_store_dwordx4 v[38:39], v[92:95], off offset:3072 nt
	s_andn2_b64 exec, exec, s[14:15]
	s_cbranch_execz .LBB0_1653
.LBB0_1651:
	v_mov_b32_e32 v32, 0
	v_mov_b32_e32 v33, 0
	v_mov_b32_e32 v34, 0
	v_mov_b32_e32 v35, 0
	s_and_saveexec_b64 s[2:3], vcc
	s_cbranch_execz .LBB0_1650
	v_lshl_add_u64 v[22:23], v[16:17], 0, v[180:181]
	global_load_dwordx4 v[32:35], v[22:23], off
	s_branch .LBB0_1650
